# GEMM K-loops: priorities inverted (loader segment prio 2, MFMA segment prio 0, trailing MFMAs prio 3); norm partial-sum load chains de-serialized
# speedup vs baseline: 1.0329x; 1.0247x over previous
; template <int MODE>
; __device__ __forceinline__ void norm_row(const Params& p, const f32x4 (&g)[8], int r, int lane, int nparts, float pscale) {
;     ...
;     if (MODE != 0 && nparts > 0 && r >= 8192) {
;         const float* pp = (const float*)(p.ws + WS_ST) + (size_t)(r - 8192) * 2048 + lane * 4;
;         f32x4 a[8];
; #pragma unroll
;         for (int i = 0; i < 8; ++i) a[i] = (f32x4){0.f, 0.f, 0.f, 0.f};
;         for (int k = 0; k < nparts; ++k) {
; #pragma unroll
;             for (int i = 0; i < 8; ++i) a[i] += *(const f32x4*)(pp + (size_t)k * (512 * 2048) + i * 256);
;         }
.LBB0_34:
	s_waitcnt vmcnt(0)
	v_lshl_add_u64 v[122:123], v[86:87], 0, s[46:47]
	v_add_co_u32_e32 v90, vcc, s37, v122
	s_mov_b32 s2, 0x2a800000
	s_nop 0
	v_addc_co_u32_e32 v91, vcc, 0, v123, vcc
	v_add_co_u32_e32 v146, vcc, s62, v122
	s_add_u32 s46, s46, 0x1000000
	s_nop 0
	v_addc_co_u32_e32 v147, vcc, 0, v123, vcc
	global_load_dwordx4 v[200:203], v[146:147], off offset:-4096
	s_addc_u32 s47, s47, 0
	s_cmp_lg_u32 s46, 0x3000000
	global_load_dwordx4 v[204:207], v[90:91], off offset:1024
	global_load_dwordx4 v[208:211], v[90:91], off offset:2048
	global_load_dwordx4 v[212:215], v[90:91], off offset:3072
	global_load_dwordx4 v[216:219], v[146:147], off
	global_load_dwordx4 v[220:223], v[146:147], off offset:1024
	global_load_dwordx4 v[224:227], v[146:147], off offset:2048
	global_load_dwordx4 v[228:231], v[146:147], off offset:3072
	s_waitcnt vmcnt(0)
	v_pk_add_f32 v[120:121], v[120:121], v[202:203]
	v_pk_add_f32 v[148:149], v[116:117], v[200:201]
	v_pk_add_f32 v[144:145], v[118:119], v[206:207]
	v_pk_add_f32 v[142:143], v[112:113], v[204:205]
	v_pk_add_f32 v[118:119], v[114:115], v[210:211]
	v_pk_add_f32 v[116:117], v[108:109], v[208:209]
	v_pk_add_f32 v[114:115], v[110:111], v[214:215]
	v_pk_add_f32 v[112:113], v[104:105], v[212:213]
	v_pk_add_f32 v[110:111], v[106:107], v[218:219]
	v_pk_add_f32 v[108:109], v[100:101], v[216:217]
	v_pk_add_f32 v[106:107], v[102:103], v[222:223]
	v_pk_add_f32 v[104:105], v[96:97], v[220:221]
	v_pk_add_f32 v[100:101], v[94:95], v[224:225]
	v_pk_add_f32 v[98:99], v[98:99], v[226:227]
	v_pk_add_f32 v[92:93], v[92:93], v[230:231]
	v_add_co_u32_e32 v96, vcc, s63, v122
	s_nop 0
	v_addc_co_u32_e32 v97, vcc, 0, v123, vcc
	v_add_co_u32_e32 v102, vcc, s26, v122
	s_nop 1
	v_addc_co_u32_e32 v103, vcc, 0, v123, vcc
	global_load_dwordx4 v[232:235], v[102:103], off offset:-4096
	global_load_dwordx4 v[236:239], v[96:97], off offset:1024
	global_load_dwordx4 v[240:243], v[96:97], off offset:2048
	global_load_dwordx4 v[244:247], v[96:97], off offset:3072
	global_load_dwordx4 v[200:203], v[102:103], off
	global_load_dwordx4 v[204:207], v[102:103], off offset:1024
	global_load_dwordx4 v[208:211], v[102:103], off offset:2048
	global_load_dwordx4 v[212:215], v[102:103], off offset:3072
	s_waitcnt vmcnt(0)
	v_pk_add_f32 v[94:95], v[88:89], v[228:229]
	v_pk_add_f32 v[120:121], v[120:121], v[234:235]
	v_pk_add_f32 v[146:147], v[148:149], v[232:233]
	v_pk_add_f32 v[144:145], v[144:145], v[238:239]
	v_pk_add_f32 v[142:143], v[142:143], v[236:237]
	v_pk_add_f32 v[148:149], v[118:119], v[242:243]
	v_pk_add_f32 v[150:151], v[116:117], v[240:241]
	v_pk_add_f32 v[96:97], v[114:115], v[246:247]
	v_pk_add_f32 v[152:153], v[112:113], v[244:245]
	v_pk_add_f32 v[154:155], v[110:111], v[202:203]
	v_pk_add_f32 v[156:157], v[108:109], v[200:201]
	v_pk_add_f32 v[158:159], v[106:107], v[206:207]
	v_pk_add_f32 v[176:177], v[104:105], v[204:205]
	v_pk_add_f32 v[178:179], v[98:99], v[210:211]
	v_pk_add_f32 v[180:181], v[100:101], v[208:209]
	v_pk_add_f32 v[182:183], v[92:93], v[214:215]
	v_add_co_u32_e32 v92, vcc, s30, v122
	s_nop 0
	v_addc_co_u32_e32 v93, vcc, 0, v123, vcc
	v_add_co_u32_e32 v186, vcc, s31, v122
	s_nop 1
	v_addc_co_u32_e32 v187, vcc, 0, v123, vcc
	global_load_dwordx4 v[216:219], v[186:187], off offset:-4096
	global_load_dwordx4 v[220:223], v[92:93], off offset:1024
	s_waitcnt vmcnt(0)
	v_pk_add_f32 v[184:185], v[94:95], v[212:213]
	v_pk_add_f32 v[116:117], v[120:121], v[218:219]
	v_pk_add_f32 v[118:119], v[146:147], v[216:217]
	v_add_co_u32_e32 v146, vcc, s2, v122
	global_load_dwordx4 v[224:227], v[92:93], off offset:2048
	global_load_dwordx4 v[228:231], v[186:187], off offset:3072
	v_addc_co_u32_e32 v147, vcc, 0, v123, vcc
	v_add_co_u32_e32 v122, vcc, s4, v122
	global_load_dwordx4 v[232:235], v[92:93], off offset:3072
	v_addc_co_u32_e32 v123, vcc, 0, v123, vcc
	global_load_dwordx4 v[236:239], v[186:187], off
	global_load_dwordx4 v[240:243], v[186:187], off offset:1024
	global_load_dwordx4 v[244:247], v[186:187], off offset:2048
	global_load_dwordx4 v[200:203], v[122:123], off offset:-4096
	global_load_dwordx4 v[204:207], v[146:147], off offset:1024
	global_load_dwordx4 v[208:211], v[146:147], off offset:2048
	global_load_dwordx4 v[212:215], v[146:147], off offset:3072
	global_load_dwordx4 v[216:219], v[122:123], off
	s_waitcnt vmcnt(0)
	v_pk_add_f32 v[112:113], v[144:145], v[222:223]
	v_pk_add_f32 v[114:115], v[142:143], v[220:221]
	v_pk_add_f32 v[108:109], v[148:149], v[226:227]
	v_pk_add_f32 v[110:111], v[150:151], v[224:225]
	v_pk_add_f32 v[104:105], v[96:97], v[234:235]
	v_pk_add_f32 v[106:107], v[152:153], v[232:233]
	v_pk_add_f32 v[100:101], v[154:155], v[238:239]
	v_pk_add_f32 v[102:103], v[156:157], v[236:237]
	v_pk_add_f32 v[96:97], v[158:159], v[242:243]
	v_pk_add_f32 v[98:99], v[176:177], v[240:241]
	v_pk_add_f32 v[92:93], v[178:179], v[246:247]
	v_pk_add_f32 v[94:95], v[180:181], v[244:245]
	v_pk_add_f32 v[88:89], v[182:183], v[230:231]
	v_pk_add_f32 v[90:91], v[184:185], v[228:229]
	v_pk_add_f32 v[120:121], v[116:117], v[202:203]
	v_pk_add_f32 v[116:117], v[118:119], v[200:201]
	v_pk_add_f32 v[118:119], v[112:113], v[206:207]
	v_pk_add_f32 v[112:113], v[114:115], v[204:205]
	v_pk_add_f32 v[114:115], v[108:109], v[210:211]
	v_pk_add_f32 v[108:109], v[110:111], v[208:209]
	v_pk_add_f32 v[110:111], v[104:105], v[214:215]
	v_pk_add_f32 v[104:105], v[106:107], v[212:213]
	v_pk_add_f32 v[106:107], v[100:101], v[218:219]
	v_pk_add_f32 v[100:101], v[102:103], v[216:217]
	global_load_dwordx4 v[220:223], v[122:123], off offset:1024
	global_load_dwordx4 v[224:227], v[122:123], off offset:2048
	global_load_dwordx4 v[228:231], v[122:123], off offset:3072
	s_waitcnt vmcnt(0)
	v_pk_add_f32 v[102:103], v[96:97], v[222:223]
	v_pk_add_f32 v[96:97], v[98:99], v[220:221]
	v_pk_add_f32 v[98:99], v[92:93], v[226:227]
	v_pk_add_f32 v[94:95], v[94:95], v[224:225]
	v_pk_add_f32 v[92:93], v[88:89], v[230:231]
	v_pk_add_f32 v[88:89], v[90:91], v[228:229]
	s_waitcnt vmcnt(0)
	v_mov_b32_e32 v142, v228
	v_mov_b32_e32 v143, v229
	v_mov_b32_e32 v144, v230
	v_mov_b32_e32 v145, v231
	s_cbranch_scc1 .LBB0_34
; template <int MODE>
; __device__ __forceinline__ void norm_row(const Params& p, const f32x4 (&g)[8], int r, int lane, int nparts, float pscale) {
;     ...
;         for (int i = 0; i < 8; ++i) { v[i] += pscale * a[i]; *(f32x4*)(X + (size_t)r * 2048 + i * 256 + lane * 4) = v[i]; }
	v_pk_add_f32 v[66:67], v[66:67], v[120:121]
	v_pk_add_f32 v[64:65], v[64:65], v[116:117]
	v_pk_add_f32 v[62:63], v[62:63], v[118:119]
	v_pk_add_f32 v[60:61], v[60:61], v[112:113]
	v_pk_add_f32 v[58:59], v[58:59], v[114:115]
	v_pk_add_f32 v[56:57], v[56:57], v[108:109]
	v_pk_add_f32 v[54:55], v[54:55], v[110:111]
	v_pk_add_f32 v[52:53], v[52:53], v[104:105]
	v_pk_add_f32 v[50:51], v[50:51], v[106:107]
	v_pk_add_f32 v[48:49], v[48:49], v[100:101]
	v_pk_add_f32 v[46:47], v[46:47], v[102:103]
	v_pk_add_f32 v[44:45], v[44:45], v[96:97]
	v_pk_add_f32 v[42:43], v[42:43], v[98:99]
	v_pk_add_f32 v[40:41], v[40:41], v[94:95]
	v_pk_add_f32 v[38:39], v[38:39], v[92:93]
	v_pk_add_f32 v[36:37], v[36:37], v[88:89]
	global_store_dwordx4 v[80:81], v[64:67], off
	global_store_dwordx4 v[80:81], v[60:63], off offset:1024
	global_store_dwordx4 v[80:81], v[56:59], off offset:2048
	global_store_dwordx4 v[80:81], v[52:55], off offset:3072
	global_store_dwordx4 v[84:85], v[48:51], off
	global_store_dwordx4 v[82:83], v[44:47], off
	global_store_dwordx4 v[78:79], v[40:43], off
	global_store_dwordx4 v[76:77], v[36:39], off
	s_branch .LBB0_31

; #define PG8_STAGE(bufoff, gbase, voff) do { _Pragma("unroll") for (int _i = 0; _i < 2; ++_i) \
;         __builtin_amdgcn_global_load_lds((const unsigned*)((const char*)(gbase) + (voff)[_i]), (LAS unsigned*)(lds + (bufoff) + ldsw + _i * 8192), 16, 0, 0); } while (0)
; #define PG8_LDA(dst, b, h) do { _Pragma("unroll") for (int m = 0; m < 4; ++m) _Pragma("unroll") for (int k = 0; k < 2; ++k) dst[m][k] = *(const LAS bf16x8*)(lds + PG8_SA(b, h) + aoff + m * 2048 + k * 1024); } while (0)
; #define PG8_LDB(dst, b, h) do { _Pragma("unroll") for (int n = 0; n < 2; ++n) _Pragma("unroll") for (int k = 0; k < 2; ++k) dst[n][k] = *(const LAS bf16x8*)(lds + PG8_SB(b, h) + boff + n * 2048 + k * 1024); } while (0)
; #define PG8_MMA(ai, bj, At, Bt) do { __builtin_amdgcn_s_setprio(1); _Pragma("unroll") for (int m = 0; m < 4; ++m) _Pragma("unroll") for (int n = 0; n < 2; ++n) _Pragma("unroll") for (int k = 0; k < 2; ++k) \
;         acc[ai][bj][m][n] = __builtin_amdgcn_mfma_f32_16x16x32_bf16(Bt[n][k], At[m][k], acc[ai][bj][m][n], 0, 0, 0); __builtin_amdgcn_s_setprio(0); } while (0)
; #define PG8_WAIT_V(n) asm volatile("s_waitcnt vmcnt(" #n ")" ::: "memory")
; #define PG8_WAIT_L(n) asm volatile("s_waitcnt lgkmcnt(" #n ")" ::: "memory")
; template <class Epi, class Sched, int LD>
; __device__ __forceinline__ void gemm_phase(LAS unsigned char* lds, const Gemm g, const Sched& S, const Epi& E) {
;     ...
;         for (int t = 0; t < nt; t += 2) {
;             const bool last = (t == nt - 2);
;             const char* a1 = cA + (size_t)(t + 1) * kstep;
;             const char* a2 = last ? nA : cA + (size_t)(t + 2) * kstep; const char* b2 = last ? nB : cB + (size_t)(t + 2) * kstep;
;             const char* a3 = a2 + kstep; const char* b3 = b2 + kstep;
;             PG8_LDB(B0, 0, 0); PG8_SCHED; PG8_LDA(At, 0, 0); PG8_STAGE(PG8_SA(1, 1), a1 + hstep, voffA);
;             PG8_WAIT_L(8); PG8_BAR; PG8_WAIT_L(0); PG8_MMA(0, 0, At, B0); PG8_BAR; PG8_SCHED;
;             PG8_LDB(B1, 0, 1); PG8_STAGE(PG8_SB(0, 0), b2, voffB);
;             PG8_BAR; PG8_WAIT_L(0); PG8_MMA(0, 1, At, B1); PG8_BAR;
;             PG8_LDA(At, 0, 1); PG8_STAGE(PG8_SA(0, 0), a2, voffA);
;             PG8_BAR; PG8_WAIT_L(0); PG8_MMA(1, 0, At, B0); PG8_BAR; PG8_SCHED;
;             PG8_STAGE(PG8_SB(0, 1), b2 + hstep, voffB);
;             PG8_WAIT_V(6); PG8_BAR; PG8_MMA(1, 1, At, B1); PG8_BAR;
.LBB0_58:
	s_add_i32 s71, s4, 2
	s_add_u32 s48, s46, 0x4000
	s_addc_u32 s5, s47, 0
	s_cmp_eq_u32 s68, s4
	s_cselect_b32 s4, s42, s48
	s_cselect_b32 s5, s43, s5
	s_cselect_b32 s48, s44, s69
	s_cselect_b32 s49, s45, s70
	s_add_u32 s50, s4, 0x8000
	s_addc_u32 s51, s5, 0
	s_add_i32 s72, 0, 0x10000
	ds_read_b128 v[140:143], v228
	ds_read_b128 v[150:153], v228 offset:1024
	ds_read_b128 v[154:157], v228 offset:2048
	ds_read_b128 v[176:179], v228 offset:3072
	s_add_i32 m0, s39, 0xc000
	ds_read_b128 v[180:183], v148
	ds_read_b128 v[184:187], v148 offset:1024
	ds_read_b128 v[188:191], v148 offset:2048
	ds_read_b128 v[192:195], v148 offset:3072
	ds_read_b128 v[196:199], v148 offset:4096
	ds_read_b128 v[200:203], v148 offset:5120
	ds_read_b128 v[204:207], v148 offset:6144
	ds_read_b128 v[208:211], v148 offset:7168
	global_load_lds_dwordx4 v132, s[46:47]
	s_add_i32 m0, s39, 0xe000
	s_nop 0
	global_load_lds_dwordx4 v138, s[46:47]
	s_waitcnt lgkmcnt(8)
	s_barrier
	s_waitcnt lgkmcnt(0)
	s_setprio 0
	v_mfma_f32_16x16x32_bf16 v[128:131], v[140:143], v[180:183], v[128:131]
	v_mfma_f32_16x16x32_bf16 v[124:127], v[154:157], v[180:183], v[124:127]
	v_mfma_f32_16x16x32_bf16 v[112:115], v[140:143], v[188:191], v[112:115]
	v_mfma_f32_16x16x32_bf16 v[108:111], v[154:157], v[188:191], v[108:111]
	v_mfma_f32_16x16x32_bf16 v[96:99], v[140:143], v[196:199], v[96:99]
	v_mfma_f32_16x16x32_bf16 v[92:95], v[154:157], v[196:199], v[92:95]
	v_mfma_f32_16x16x32_bf16 v[80:83], v[140:143], v[204:207], v[80:83]
	v_mfma_f32_16x16x32_bf16 v[76:79], v[154:157], v[204:207], v[76:79]
	v_mfma_f32_16x16x32_bf16 v[128:131], v[150:153], v[184:187], v[128:131]
	v_mfma_f32_16x16x32_bf16 v[124:127], v[176:179], v[184:187], v[124:127]
	v_mfma_f32_16x16x32_bf16 v[112:115], v[150:153], v[192:195], v[112:115]
	v_mfma_f32_16x16x32_bf16 v[108:111], v[176:179], v[192:195], v[108:111]
	v_mfma_f32_16x16x32_bf16 v[96:99], v[150:153], v[200:203], v[96:99]
	v_mfma_f32_16x16x32_bf16 v[92:95], v[176:179], v[200:203], v[92:95]
	s_setprio 3
	s_barrier
	v_mfma_f32_16x16x32_bf16 v[80:83], v[150:153], v[208:211], v[80:83]
	v_mfma_f32_16x16x32_bf16 v[76:79], v[176:179], v[208:211], v[76:79]
	s_setprio 2
	s_add_i32 s74, 0, 0x14000
	s_add_i32 s72, s72, s29
	ds_read_b128 v[212:215], v228 offset:16384
	ds_read_b128 v[216:219], v228 offset:17408
	ds_read_b128 v[220:223], v228 offset:18432
	ds_read_b128 v[224:227], v228 offset:19456
	s_mov_b32 m0, s72
	s_nop 0
	global_load_lds_dwordx4 v132, s[48:49]
	s_add_i32 m0, s72, 0x2000
	s_nop 0
	global_load_lds_dwordx4 v138, s[48:49]
	s_barrier
	s_waitcnt lgkmcnt(0)
	s_setprio 0
	v_mfma_f32_16x16x32_bf16 v[120:123], v[212:215], v[180:183], v[120:123]
	v_mfma_f32_16x16x32_bf16 v[116:119], v[220:223], v[180:183], v[116:119]
	v_mfma_f32_16x16x32_bf16 v[104:107], v[212:215], v[188:191], v[104:107]
	v_mfma_f32_16x16x32_bf16 v[100:103], v[220:223], v[188:191], v[100:103]
	v_mfma_f32_16x16x32_bf16 v[88:91], v[212:215], v[196:199], v[88:91]
	v_mfma_f32_16x16x32_bf16 v[84:87], v[220:223], v[196:199], v[84:87]
	v_mfma_f32_16x16x32_bf16 v[72:75], v[212:215], v[204:207], v[72:75]
	v_mfma_f32_16x16x32_bf16 v[68:71], v[220:223], v[204:207], v[68:71]
	v_mfma_f32_16x16x32_bf16 v[120:123], v[216:219], v[184:187], v[120:123]
	v_mfma_f32_16x16x32_bf16 v[116:119], v[224:227], v[184:187], v[116:119]
	v_mfma_f32_16x16x32_bf16 v[104:107], v[216:219], v[192:195], v[104:107]
	v_mfma_f32_16x16x32_bf16 v[100:103], v[224:227], v[192:195], v[100:103]
	v_mfma_f32_16x16x32_bf16 v[88:91], v[216:219], v[200:203], v[88:91]
	v_mfma_f32_16x16x32_bf16 v[84:87], v[224:227], v[200:203], v[84:87]
	v_mfma_f32_16x16x32_bf16 v[72:75], v[216:219], v[208:211], v[72:75]
	v_mfma_f32_16x16x32_bf16 v[68:71], v[224:227], v[208:211], v[68:71]
	s_setprio 2
	s_mov_b32 m0, s39
	s_barrier
	ds_read_b128 v[180:183], v148 offset:16384
	ds_read_b128 v[184:187], v148 offset:17408
	ds_read_b128 v[188:191], v148 offset:18432
	ds_read_b128 v[192:195], v148 offset:19456
	ds_read_b128 v[196:199], v148 offset:20480
	ds_read_b128 v[200:203], v148 offset:21504
	ds_read_b128 v[204:207], v148 offset:22528
	ds_read_b128 v[208:211], v148 offset:23552
	global_load_lds_dwordx4 v132, s[4:5]
	s_mov_b32 m0, s52
	s_nop 0
	global_load_lds_dwordx4 v138, s[4:5]
	s_barrier
	s_waitcnt lgkmcnt(0)
	s_setprio 0
	v_mfma_f32_16x16x32_bf16 v[64:67], v[140:143], v[180:183], v[64:67]
	v_mfma_f32_16x16x32_bf16 v[60:63], v[154:157], v[180:183], v[60:63]
	v_mfma_f32_16x16x32_bf16 v[48:51], v[140:143], v[188:191], v[48:51]
	v_mfma_f32_16x16x32_bf16 v[44:47], v[154:157], v[188:191], v[44:47]
	v_mfma_f32_16x16x32_bf16 v[32:35], v[140:143], v[196:199], v[32:35]
	v_mfma_f32_16x16x32_bf16 v[28:31], v[154:157], v[196:199], v[28:31]
	v_mfma_f32_16x16x32_bf16 v[16:19], v[140:143], v[204:207], v[16:19]
	v_mfma_f32_16x16x32_bf16 v[12:15], v[154:157], v[204:207], v[12:15]
	v_mfma_f32_16x16x32_bf16 v[64:67], v[150:153], v[184:187], v[64:67]
	v_mfma_f32_16x16x32_bf16 v[60:63], v[176:179], v[184:187], v[60:63]
	v_mfma_f32_16x16x32_bf16 v[48:51], v[150:153], v[192:195], v[48:51]
	v_mfma_f32_16x16x32_bf16 v[44:47], v[176:179], v[192:195], v[44:47]
	v_mfma_f32_16x16x32_bf16 v[32:35], v[150:153], v[200:203], v[32:35]
	v_mfma_f32_16x16x32_bf16 v[28:31], v[176:179], v[200:203], v[28:31]
	s_setprio 3
	s_barrier
	v_mfma_f32_16x16x32_bf16 v[16:19], v[150:153], v[208:211], v[16:19]
	v_mfma_f32_16x16x32_bf16 v[12:15], v[176:179], v[208:211], v[12:15]
	s_setprio 2
	s_add_u32 s72, s48, 0x4000
	s_addc_u32 s73, s49, 0
	s_add_i32 s74, s74, s29
	s_mov_b32 m0, s74
	s_nop 0
	global_load_lds_dwordx4 v132, s[72:73]
	s_add_i32 m0, s74, 0x2000
	s_nop 0
	global_load_lds_dwordx4 v138, s[72:73]
	s_waitcnt vmcnt(6)
	s_barrier
; #define PG8_STAGE(bufoff, gbase, voff) do { _Pragma("unroll") for (int _i = 0; _i < 2; ++_i) \
;         __builtin_amdgcn_global_load_lds((const unsigned*)((const char*)(gbase) + (voff)[_i]), (LAS unsigned*)(lds + (bufoff) + ldsw + _i * 8192), 16, 0, 0); } while (0)
; #define PG8_LDA(dst, b, h) do { _Pragma("unroll") for (int m = 0; m < 4; ++m) _Pragma("unroll") for (int k = 0; k < 2; ++k) dst[m][k] = *(const LAS bf16x8*)(lds + PG8_SA(b, h) + aoff + m * 2048 + k * 1024); } while (0)
; #define PG8_LDB(dst, b, h) do { _Pragma("unroll") for (int n = 0; n < 2; ++n) _Pragma("unroll") for (int k = 0; k < 2; ++k) dst[n][k] = *(const LAS bf16x8*)(lds + PG8_SB(b, h) + boff + n * 2048 + k * 1024); } while (0)
; #define PG8_MMA(ai, bj, At, Bt) do { __builtin_amdgcn_s_setprio(1); _Pragma("unroll") for (int m = 0; m < 4; ++m) _Pragma("unroll") for (int n = 0; n < 2; ++n) _Pragma("unroll") for (int k = 0; k < 2; ++k) \
;         acc[ai][bj][m][n] = __builtin_amdgcn_mfma_f32_16x16x32_bf16(Bt[n][k], At[m][k], acc[ai][bj][m][n], 0, 0, 0); __builtin_amdgcn_s_setprio(0); } while (0)
; #define PG8_WAIT_V(n) asm volatile("s_waitcnt vmcnt(" #n ")" ::: "memory")
; #define PG8_WAIT_L(n) asm volatile("s_waitcnt lgkmcnt(" #n ")" ::: "memory")
; #define PG8_BAR __builtin_amdgcn_s_barrier()
; #define PG8_SCHED __builtin_amdgcn_sched_barrier(0)
; template <class Epi, class Sched, int LD>
; __device__ __forceinline__ void gemm_phase(LAS unsigned char* lds, const Gemm g, const Sched& S, const Epi& E) {
;     ...
;             PG8_WAIT_V(6); PG8_BAR; PG8_MMA(1, 1, At, B1); PG8_BAR;
;             PG8_LDB(B0, 1, 0); PG8_SCHED; PG8_LDA(At, 1, 0); PG8_STAGE(PG8_SA(0, 1), a2 + hstep, voffA);
;             PG8_WAIT_L(8); PG8_BAR; PG8_WAIT_L(0); PG8_MMA(0, 0, At, B0); PG8_BAR; PG8_SCHED;
;             PG8_LDB(B1, 1, 1); PG8_STAGE(PG8_SB(1, 0), b3, voffB);
;             PG8_BAR; PG8_WAIT_L(0); PG8_MMA(0, 1, At, B1); PG8_BAR;
	s_setprio 0
	v_mfma_f32_16x16x32_bf16 v[56:59], v[212:215], v[180:183], v[56:59]
	v_mfma_f32_16x16x32_bf16 v[52:55], v[220:223], v[180:183], v[52:55]
	v_mfma_f32_16x16x32_bf16 v[40:43], v[212:215], v[188:191], v[40:43]
	v_mfma_f32_16x16x32_bf16 v[36:39], v[220:223], v[188:191], v[36:39]
	v_mfma_f32_16x16x32_bf16 v[24:27], v[212:215], v[196:199], v[24:27]
	v_mfma_f32_16x16x32_bf16 v[20:23], v[220:223], v[196:199], v[20:23]
	v_mfma_f32_16x16x32_bf16 v[8:11], v[212:215], v[204:207], v[8:11]
	v_mfma_f32_16x16x32_bf16 v[4:7], v[220:223], v[204:207], v[4:7]
	v_mfma_f32_16x16x32_bf16 v[56:59], v[216:219], v[184:187], v[56:59]
	v_mfma_f32_16x16x32_bf16 v[52:55], v[224:227], v[184:187], v[52:55]
	v_mfma_f32_16x16x32_bf16 v[40:43], v[216:219], v[192:195], v[40:43]
	v_mfma_f32_16x16x32_bf16 v[36:39], v[224:227], v[192:195], v[36:39]
	v_mfma_f32_16x16x32_bf16 v[24:27], v[216:219], v[200:203], v[24:27]
	v_mfma_f32_16x16x32_bf16 v[20:23], v[224:227], v[200:203], v[20:23]
	v_mfma_f32_16x16x32_bf16 v[8:11], v[216:219], v[208:211], v[8:11]
	v_mfma_f32_16x16x32_bf16 v[4:7], v[224:227], v[208:211], v[4:7]
	s_setprio 2
	s_add_i32 s72, 0, 0x18000
	s_barrier
	ds_read_b128 v[140:143], v228 offset:32768
	ds_read_b128 v[150:153], v228 offset:33792
	ds_read_b128 v[154:157], v228 offset:34816
	ds_read_b128 v[176:179], v228 offset:35840
	s_add_u32 s4, s4, 0x4000
	s_addc_u32 s5, s5, 0
	s_mov_b32 m0, s53
	ds_read_b128 v[180:183], v148 offset:32768
	ds_read_b128 v[184:187], v148 offset:33792
	ds_read_b128 v[188:191], v148 offset:34816
	ds_read_b128 v[192:195], v148 offset:35840
	ds_read_b128 v[196:199], v148 offset:36864
	ds_read_b128 v[200:203], v148 offset:37888
	ds_read_b128 v[204:207], v148 offset:38912
	ds_read_b128 v[208:211], v148 offset:39936
	global_load_lds_dwordx4 v132, s[4:5]
	s_mov_b32 m0, s54
	s_nop 0
	global_load_lds_dwordx4 v138, s[4:5]
	s_waitcnt lgkmcnt(8)
	s_barrier
	s_waitcnt lgkmcnt(0)
	s_setprio 0
	v_mfma_f32_16x16x32_bf16 v[128:131], v[140:143], v[180:183], v[128:131]
	v_mfma_f32_16x16x32_bf16 v[124:127], v[154:157], v[180:183], v[124:127]
	v_mfma_f32_16x16x32_bf16 v[112:115], v[140:143], v[188:191], v[112:115]
	v_mfma_f32_16x16x32_bf16 v[108:111], v[154:157], v[188:191], v[108:111]
	v_mfma_f32_16x16x32_bf16 v[96:99], v[140:143], v[196:199], v[96:99]
	v_mfma_f32_16x16x32_bf16 v[92:95], v[154:157], v[196:199], v[92:95]
	v_mfma_f32_16x16x32_bf16 v[80:83], v[140:143], v[204:207], v[80:83]
	v_mfma_f32_16x16x32_bf16 v[76:79], v[154:157], v[204:207], v[76:79]
	v_mfma_f32_16x16x32_bf16 v[128:131], v[150:153], v[184:187], v[128:131]
	v_mfma_f32_16x16x32_bf16 v[124:127], v[176:179], v[184:187], v[124:127]
	v_mfma_f32_16x16x32_bf16 v[112:115], v[150:153], v[192:195], v[112:115]
	v_mfma_f32_16x16x32_bf16 v[108:111], v[176:179], v[192:195], v[108:111]
	v_mfma_f32_16x16x32_bf16 v[96:99], v[150:153], v[200:203], v[96:99]
	v_mfma_f32_16x16x32_bf16 v[92:95], v[176:179], v[200:203], v[92:95]
	s_setprio 3
	s_barrier
	v_mfma_f32_16x16x32_bf16 v[80:83], v[150:153], v[208:211], v[80:83]
	v_mfma_f32_16x16x32_bf16 v[76:79], v[176:179], v[208:211], v[76:79]
	s_setprio 2
	s_add_i32 s73, 0, 0x1c000
	s_add_u32 s4, s48, 0x8000
	s_addc_u32 s5, s49, 0
	s_add_i32 s72, s72, s29
	ds_read_b128 v[212:215], v228 offset:49152
	ds_read_b128 v[216:219], v228 offset:50176
	ds_read_b128 v[220:223], v228 offset:51200
	ds_read_b128 v[224:227], v228 offset:52224
	s_mov_b32 m0, s72
	s_nop 0
	global_load_lds_dwordx4 v132, s[4:5]
	s_add_i32 m0, s72, 0x2000
	s_nop 0
	global_load_lds_dwordx4 v138, s[4:5]
	s_barrier
	s_waitcnt lgkmcnt(0)
	s_setprio 0
	v_mfma_f32_16x16x32_bf16 v[120:123], v[212:215], v[180:183], v[120:123]
	v_mfma_f32_16x16x32_bf16 v[116:119], v[220:223], v[180:183], v[116:119]
	v_mfma_f32_16x16x32_bf16 v[104:107], v[212:215], v[188:191], v[104:107]
	v_mfma_f32_16x16x32_bf16 v[100:103], v[220:223], v[188:191], v[100:103]
	v_mfma_f32_16x16x32_bf16 v[88:91], v[212:215], v[196:199], v[88:91]
	v_mfma_f32_16x16x32_bf16 v[84:87], v[220:223], v[196:199], v[84:87]
	v_mfma_f32_16x16x32_bf16 v[72:75], v[212:215], v[204:207], v[72:75]
	v_mfma_f32_16x16x32_bf16 v[68:71], v[220:223], v[204:207], v[68:71]
	v_mfma_f32_16x16x32_bf16 v[120:123], v[216:219], v[184:187], v[120:123]
	v_mfma_f32_16x16x32_bf16 v[116:119], v[224:227], v[184:187], v[116:119]
	v_mfma_f32_16x16x32_bf16 v[104:107], v[216:219], v[192:195], v[104:107]
	v_mfma_f32_16x16x32_bf16 v[100:103], v[224:227], v[192:195], v[100:103]
	v_mfma_f32_16x16x32_bf16 v[88:91], v[216:219], v[200:203], v[88:91]
	v_mfma_f32_16x16x32_bf16 v[84:87], v[224:227], v[200:203], v[84:87]
	v_mfma_f32_16x16x32_bf16 v[72:75], v[216:219], v[208:211], v[72:75]
	v_mfma_f32_16x16x32_bf16 v[68:71], v[224:227], v[208:211], v[68:71]
	s_setprio 2
	s_mov_b32 m0, s55
	s_barrier
	ds_read_b128 v[180:183], v148 offset:49152
	ds_read_b128 v[184:187], v148 offset:50176
	ds_read_b128 v[188:191], v148 offset:51200
	ds_read_b128 v[192:195], v148 offset:52224
	ds_read_b128 v[196:199], v148 offset:53248
	ds_read_b128 v[200:203], v148 offset:54272
	ds_read_b128 v[204:207], v148 offset:55296
	ds_read_b128 v[208:211], v148 offset:56320
	global_load_lds_dwordx4 v132, s[50:51]
	s_mov_b32 m0, s56
	s_nop 0
	global_load_lds_dwordx4 v138, s[50:51]
	s_barrier
; #define PG8_STAGE(bufoff, gbase, voff) do { _Pragma("unroll") for (int _i = 0; _i < 2; ++_i) \
;         __builtin_amdgcn_global_load_lds((const unsigned*)((const char*)(gbase) + (voff)[_i]), (LAS unsigned*)(lds + (bufoff) + ldsw + _i * 8192), 16, 0, 0); } while (0)
; #define PG8_MMA(ai, bj, At, Bt) do { __builtin_amdgcn_s_setprio(1); _Pragma("unroll") for (int m = 0; m < 4; ++m) _Pragma("unroll") for (int n = 0; n < 2; ++n) _Pragma("unroll") for (int k = 0; k < 2; ++k) \
;         acc[ai][bj][m][n] = __builtin_amdgcn_mfma_f32_16x16x32_bf16(Bt[n][k], At[m][k], acc[ai][bj][m][n], 0, 0, 0); __builtin_amdgcn_s_setprio(0); } while (0)
; #define PG8_WAIT_V(n) asm volatile("s_waitcnt vmcnt(" #n ")" ::: "memory")
; #define PG8_WAIT_L(n) asm volatile("s_waitcnt lgkmcnt(" #n ")" ::: "memory")
; #define PG8_BAR __builtin_amdgcn_s_barrier()
; #define PG8_SCHED __builtin_amdgcn_sched_barrier(0)
;     __device__ __forceinline__ void operator()(const f32x4 (&acc)[2][2][4][2], const Unit& u, int wr, int wc, int fr, int fq) const {
;     ...
;         } else {
;             float* base = PART + (size_t)u.part * (512 * 2048);
; #pragma unroll
;             for (int ai = 0; ai < 2; ++ai)
; #pragma unroll
;                 for (int m = 0; m < 4; ++m) {
;                     float* rowp = base + (size_t)(row0 - 8192 + ai * HALF + m * 16) * D_MODEL + col0;
; #pragma unroll
;                     for (int bj = 0; bj < 2; ++bj)
; #pragma unroll
;                         for (int n = 0; n < 2; ++n) *(f32x4*)(rowp + bj * HALF + n * 16) = acc[ai][bj][m][n];
;                 }
; template <class Epi, class Sched, int LD>
; __device__ __forceinline__ void gemm_phase(LAS unsigned char* lds, const Gemm g, const Sched& S, const Epi& E) {
;     ...
;             PG8_BAR; PG8_WAIT_L(0); PG8_MMA(1, 0, At, B0); PG8_BAR; PG8_SCHED;
;             PG8_STAGE(PG8_SB(1, 1), b3 + hstep, voffB);
;             PG8_WAIT_V(6); PG8_BAR; PG8_MMA(1, 1, At, B1); PG8_BAR;
	s_waitcnt lgkmcnt(0)
	s_setprio 0
	v_mfma_f32_16x16x32_bf16 v[64:67], v[140:143], v[180:183], v[64:67]
	v_mfma_f32_16x16x32_bf16 v[60:63], v[154:157], v[180:183], v[60:63]
	v_mfma_f32_16x16x32_bf16 v[48:51], v[140:143], v[188:191], v[48:51]
	v_mfma_f32_16x16x32_bf16 v[44:47], v[154:157], v[188:191], v[44:47]
	v_mfma_f32_16x16x32_bf16 v[32:35], v[140:143], v[196:199], v[32:35]
	v_mfma_f32_16x16x32_bf16 v[28:31], v[154:157], v[196:199], v[28:31]
	v_mfma_f32_16x16x32_bf16 v[16:19], v[140:143], v[204:207], v[16:19]
	v_mfma_f32_16x16x32_bf16 v[12:15], v[154:157], v[204:207], v[12:15]
	v_mfma_f32_16x16x32_bf16 v[64:67], v[150:153], v[184:187], v[64:67]
	v_mfma_f32_16x16x32_bf16 v[60:63], v[176:179], v[184:187], v[60:63]
	v_mfma_f32_16x16x32_bf16 v[48:51], v[150:153], v[192:195], v[48:51]
	v_mfma_f32_16x16x32_bf16 v[44:47], v[176:179], v[192:195], v[44:47]
	v_mfma_f32_16x16x32_bf16 v[32:35], v[150:153], v[200:203], v[32:35]
	v_mfma_f32_16x16x32_bf16 v[28:31], v[176:179], v[200:203], v[28:31]
	s_setprio 3
	s_barrier
	v_mfma_f32_16x16x32_bf16 v[16:19], v[150:153], v[208:211], v[16:19]
	v_mfma_f32_16x16x32_bf16 v[12:15], v[176:179], v[208:211], v[12:15]
	s_setprio 2
	s_add_u32 s4, s48, 0xc000
	s_addc_u32 s5, s49, 0
	s_add_i32 s48, s73, s29
	s_mov_b32 m0, s48
	s_nop 0
	global_load_lds_dwordx4 v132, s[4:5]
	s_add_i32 m0, s48, 0x2000
	s_nop 0
	global_load_lds_dwordx4 v138, s[4:5]
	s_waitcnt vmcnt(6)
	s_barrier
	s_setprio 0
	v_mfma_f32_16x16x32_bf16 v[56:59], v[212:215], v[180:183], v[56:59]
	v_mfma_f32_16x16x32_bf16 v[52:55], v[220:223], v[180:183], v[52:55]
	v_mfma_f32_16x16x32_bf16 v[40:43], v[212:215], v[188:191], v[40:43]
	v_mfma_f32_16x16x32_bf16 v[36:39], v[220:223], v[188:191], v[36:39]
	v_mfma_f32_16x16x32_bf16 v[24:27], v[212:215], v[196:199], v[24:27]
	v_mfma_f32_16x16x32_bf16 v[20:23], v[220:223], v[196:199], v[20:23]
	v_mfma_f32_16x16x32_bf16 v[8:11], v[212:215], v[204:207], v[8:11]
	v_mfma_f32_16x16x32_bf16 v[4:7], v[220:223], v[204:207], v[4:7]
	v_mfma_f32_16x16x32_bf16 v[56:59], v[216:219], v[184:187], v[56:59]
	v_mfma_f32_16x16x32_bf16 v[52:55], v[224:227], v[184:187], v[52:55]
	v_mfma_f32_16x16x32_bf16 v[40:43], v[216:219], v[192:195], v[40:43]
	v_mfma_f32_16x16x32_bf16 v[36:39], v[224:227], v[192:195], v[36:39]
	v_mfma_f32_16x16x32_bf16 v[24:27], v[216:219], v[200:203], v[24:27]
	v_mfma_f32_16x16x32_bf16 v[20:23], v[224:227], v[200:203], v[20:23]
	v_mfma_f32_16x16x32_bf16 v[8:11], v[216:219], v[208:211], v[8:11]
	v_mfma_f32_16x16x32_bf16 v[4:7], v[224:227], v[208:211], v[4:7]
	s_setprio 2
	s_add_u32 s46, s46, 0x10000
	s_addc_u32 s47, s47, 0
	s_add_u32 s69, s69, 0x10000
	s_addc_u32 s70, s70, 0
	s_cmp_ge_i32 s71, s65
	s_mov_b32 s4, s71
	s_barrier
	s_cbranch_scc0 .LBB0_58
	s_setprio 0
	v_lshl_add_u32 v142, s67, 8, v137
	v_lshl_or_b32 v140, s66, 8, v147
	s_mov_b64 s[4:5], -1
	s_cmp_gt_i32 s18, -1
	v_ashrrev_i32_e32 v141, 31, v140
	v_ashrrev_i32_e32 v143, 31, v142
	s_cbranch_scc0 .LBB0_61
	s_lshl_b64 s[4:5], s[18:19], 22
	v_readlane_b32 s18, v252, 10
	s_add_u32 s4, s18, s4
	v_readlane_b32 s18, v252, 11
	s_addc_u32 s5, s18, s5
	v_lshl_add_u64 v[144:145], v[140:141], 2, s[4:5]
	v_lshlrev_b64 v[150:151], 13, v[142:143]
	s_brev_b32 s4, 63
	v_lshl_add_u64 v[144:145], v[144:145], 0, v[150:151]
	s_mov_b32 s5, -1
	v_lshl_add_u64 v[150:151], v[144:145], 0, s[4:5]
	s_brev_b32 s4, 63
	v_add_co_u32_e32 v152, vcc, s4, v144
	s_mov_b32 s4, 0xfc020000
	s_nop 0
	v_addc_co_u32_e32 v153, vcc, -1, v145, vcc
	s_mov_b32 s5, -1
	global_store_dwordx4 v[152:153], v[128:131], off
	global_store_dwordx4 v[150:151], v[124:127], off offset:64
	global_store_dwordx4 v[150:151], v[120:123], off offset:512
	global_store_dwordx4 v[150:151], v[116:119], off offset:576
	v_lshl_add_u64 v[150:151], v[144:145], 0, s[4:5]
	s_mov_b32 s4, 0xfc020000
	v_add_co_u32_e32 v152, vcc, s4, v144
	s_mov_b32 s4, 0xfc040000
	s_nop 0
	v_addc_co_u32_e32 v153, vcc, -1, v145, vcc
	s_mov_b32 s5, -1
	global_store_dwordx4 v[152:153], v[112:115], off
	global_store_dwordx4 v[150:151], v[108:111], off offset:64
	global_store_dwordx4 v[150:151], v[104:107], off offset:512
	global_store_dwordx4 v[150:151], v[100:103], off offset:576
	v_lshl_add_u64 v[150:151], v[144:145], 0, s[4:5]
	s_mov_b32 s4, 0xfc040000
	v_add_co_u32_e32 v152, vcc, s4, v144
	s_mov_b32 s4, 0xfc060000
	s_nop 0
	v_addc_co_u32_e32 v153, vcc, -1, v145, vcc
	s_mov_b32 s5, -1
	global_store_dwordx4 v[152:153], v[96:99], off
	global_store_dwordx4 v[150:151], v[92:95], off offset:64
	global_store_dwordx4 v[150:151], v[88:91], off offset:512
	global_store_dwordx4 v[150:151], v[84:87], off offset:576
	v_lshl_add_u64 v[150:151], v[144:145], 0, s[4:5]
	s_mov_b32 s4, 0xfc060000
	v_add_co_u32_e32 v152, vcc, s4, v144
	s_mov_b32 s4, 0xfc100000
	s_nop 0
	v_addc_co_u32_e32 v153, vcc, -1, v145, vcc
	s_mov_b32 s5, -1
	global_store_dwordx4 v[152:153], v[80:83], off
	global_store_dwordx4 v[150:151], v[76:79], off offset:64
	global_store_dwordx4 v[150:151], v[72:75], off offset:512
	global_store_dwordx4 v[150:151], v[68:71], off offset:576
	v_lshl_add_u64 v[150:151], v[144:145], 0, s[4:5]
	s_mov_b32 s4, 0xfc100000
	v_add_co_u32_e32 v152, vcc, s4, v144
	s_mov_b32 s4, 0xfc120000
	s_nop 0
	v_addc_co_u32_e32 v153, vcc, -1, v145, vcc
	s_mov_b32 s5, -1
	global_store_dwordx4 v[152:153], v[64:67], off
	global_store_dwordx4 v[150:151], v[60:63], off offset:64
	global_store_dwordx4 v[150:151], v[56:59], off offset:512
	global_store_dwordx4 v[150:151], v[52:55], off offset:576
	v_lshl_add_u64 v[150:151], v[144:145], 0, s[4:5]
	s_mov_b32 s4, 0xfc120000
	v_add_co_u32_e32 v152, vcc, s4, v144
	s_mov_b32 s4, 0xfc140000
	s_nop 0
	v_addc_co_u32_e32 v153, vcc, -1, v145, vcc
	s_mov_b32 s5, -1
	global_store_dwordx4 v[152:153], v[48:51], off
	global_store_dwordx4 v[150:151], v[44:47], off offset:64
	global_store_dwordx4 v[150:151], v[40:43], off offset:512
	global_store_dwordx4 v[150:151], v[36:39], off offset:576
	v_lshl_add_u64 v[150:151], v[144:145], 0, s[4:5]
	s_mov_b32 s4, 0xfc140000
	v_add_co_u32_e32 v152, vcc, s4, v144
	s_mov_b32 s4, 0xfc160000
	s_nop 0
	v_addc_co_u32_e32 v153, vcc, -1, v145, vcc
	s_mov_b32 s5, -1
	global_store_dwordx4 v[152:153], v[32:35], off
	global_store_dwordx4 v[150:151], v[28:31], off offset:64
	global_store_dwordx4 v[150:151], v[24:27], off offset:512
	global_store_dwordx4 v[150:151], v[20:23], off offset:576
	v_lshl_add_u64 v[150:151], v[144:145], 0, s[4:5]
	v_add_co_u32_e32 v144, vcc, 0xfc160000, v144
	s_mov_b64 s[4:5], 0
	s_nop 0
	v_addc_co_u32_e32 v145, vcc, -1, v145, vcc
	global_store_dwordx4 v[144:145], v[16:19], off
	global_store_dwordx4 v[150:151], v[12:15], off offset:64
	global_store_dwordx4 v[150:151], v[8:11], off offset:512
	global_store_dwordx4 v[150:151], v[4:7], off offset:576

; #define PG8_STAGE(bufoff, gbase, voff) do { _Pragma("unroll") for (int _i = 0; _i < 2; ++_i) \
;         __builtin_amdgcn_global_load_lds((const unsigned*)((const char*)(gbase) + (voff)[_i]), (LAS unsigned*)(lds + (bufoff) + ldsw + _i * 8192), 16, 0, 0); } while (0)
; #define PG8_LDA(dst, b, h) do { _Pragma("unroll") for (int m = 0; m < 4; ++m) _Pragma("unroll") for (int k = 0; k < 2; ++k) dst[m][k] = *(const LAS bf16x8*)(lds + PG8_SA(b, h) + aoff + m * 2048 + k * 1024); } while (0)
; #define PG8_LDB(dst, b, h) do { _Pragma("unroll") for (int n = 0; n < 2; ++n) _Pragma("unroll") for (int k = 0; k < 2; ++k) dst[n][k] = *(const LAS bf16x8*)(lds + PG8_SB(b, h) + boff + n * 2048 + k * 1024); } while (0)
; #define PG8_MMA(ai, bj, At, Bt) do { __builtin_amdgcn_s_setprio(1); _Pragma("unroll") for (int m = 0; m < 4; ++m) _Pragma("unroll") for (int n = 0; n < 2; ++n) _Pragma("unroll") for (int k = 0; k < 2; ++k) \
;         acc[ai][bj][m][n] = __builtin_amdgcn_mfma_f32_16x16x32_bf16(Bt[n][k], At[m][k], acc[ai][bj][m][n], 0, 0, 0); __builtin_amdgcn_s_setprio(0); } while (0)
; #define PG8_WAIT_V(n) asm volatile("s_waitcnt vmcnt(" #n ")" ::: "memory")
; #define PG8_WAIT_L(n) asm volatile("s_waitcnt lgkmcnt(" #n ")" ::: "memory")
; template <class Epi, class Sched, int LD>
; __device__ __forceinline__ void gemm_phase(LAS unsigned char* lds, const Gemm g, const Sched& S, const Epi& E) {
;     ...
;         for (int t = 0; t < nt; t += 2) {
;             const bool last = (t == nt - 2);
;             const char* a1 = cA + (size_t)(t + 1) * kstep;
;             const char* a2 = last ? nA : cA + (size_t)(t + 2) * kstep; const char* b2 = last ? nB : cB + (size_t)(t + 2) * kstep;
;             const char* a3 = a2 + kstep; const char* b3 = b2 + kstep;
;             PG8_LDB(B0, 0, 0); PG8_SCHED; PG8_LDA(At, 0, 0); PG8_STAGE(PG8_SA(1, 1), a1 + hstep, voffA);
;             PG8_WAIT_L(8); PG8_BAR; PG8_WAIT_L(0); PG8_MMA(0, 0, At, B0); PG8_BAR; PG8_SCHED;
;             PG8_LDB(B1, 0, 1); PG8_STAGE(PG8_SB(0, 0), b2, voffB);
;             PG8_BAR; PG8_WAIT_L(0); PG8_MMA(0, 1, At, B1); PG8_BAR;
;             PG8_LDA(At, 0, 1); PG8_STAGE(PG8_SA(0, 0), a2, voffA);
;             PG8_BAR; PG8_WAIT_L(0); PG8_MMA(1, 0, At, B0); PG8_BAR; PG8_SCHED;
;             PG8_STAGE(PG8_SB(0, 1), b2 + hstep, voffB);
;             PG8_WAIT_V(6); PG8_BAR; PG8_MMA(1, 1, At, B1); PG8_BAR;
.LBB0_501:
	s_add_u32 s4, s54, 0x4000
	s_addc_u32 s5, s55, 0
	s_cmp_eq_u32 s49, 28
	s_cselect_b32 s4, s50, s4
	s_cselect_b32 s5, s51, s5
	s_cselect_b32 s56, s40, s29
	s_cselect_b32 s57, s41, s47
	s_add_u32 s58, s4, 0x8000
	s_addc_u32 s59, s5, 0
	s_add_i32 s69, 0, 0x10000
	ds_read_b128 v[148:151], v228
	ds_read_b128 v[152:155], v228 offset:1024
	ds_read_b128 v[156:159], v228 offset:2048
	ds_read_b128 v[176:179], v228 offset:3072
	s_add_i32 m0, s52, 0xc000
	ds_read_b128 v[180:183], v146
	ds_read_b128 v[184:187], v146 offset:1024
	ds_read_b128 v[188:191], v146 offset:2048
	ds_read_b128 v[192:195], v146 offset:3072
	ds_read_b128 v[196:199], v146 offset:4096
	ds_read_b128 v[200:203], v146 offset:5120
	ds_read_b128 v[204:207], v146 offset:6144
	ds_read_b128 v[208:211], v146 offset:7168
	global_load_lds_dwordx4 v132, s[54:55]
	s_add_i32 m0, s52, 0xe000
	s_nop 0
	global_load_lds_dwordx4 v138, s[54:55]
	s_waitcnt lgkmcnt(8)
	s_barrier
	s_waitcnt lgkmcnt(0)
	s_setprio 0
	v_mfma_f32_16x16x32_bf16 v[128:131], v[148:151], v[180:183], v[128:131]
	v_mfma_f32_16x16x32_bf16 v[124:127], v[156:159], v[180:183], v[124:127]
	v_mfma_f32_16x16x32_bf16 v[120:123], v[148:151], v[188:191], v[120:123]
	v_mfma_f32_16x16x32_bf16 v[116:119], v[156:159], v[188:191], v[116:119]
	v_mfma_f32_16x16x32_bf16 v[104:107], v[148:151], v[196:199], v[104:107]
	v_mfma_f32_16x16x32_bf16 v[100:103], v[156:159], v[196:199], v[100:103]
	v_mfma_f32_16x16x32_bf16 v[88:91], v[148:151], v[204:207], v[88:91]
	v_mfma_f32_16x16x32_bf16 v[84:87], v[156:159], v[204:207], v[84:87]
	v_mfma_f32_16x16x32_bf16 v[128:131], v[152:155], v[184:187], v[128:131]
	v_mfma_f32_16x16x32_bf16 v[124:127], v[176:179], v[184:187], v[124:127]
	v_mfma_f32_16x16x32_bf16 v[120:123], v[152:155], v[192:195], v[120:123]
	v_mfma_f32_16x16x32_bf16 v[116:119], v[176:179], v[192:195], v[116:119]
	v_mfma_f32_16x16x32_bf16 v[104:107], v[152:155], v[200:203], v[104:107]
	v_mfma_f32_16x16x32_bf16 v[100:103], v[176:179], v[200:203], v[100:103]
	s_setprio 3
	s_barrier
	v_mfma_f32_16x16x32_bf16 v[88:91], v[152:155], v[208:211], v[88:91]
	v_mfma_f32_16x16x32_bf16 v[84:87], v[176:179], v[208:211], v[84:87]
	s_setprio 2
	s_add_i32 s72, 0, 0x14000
	s_add_i32 s69, s69, s39
	ds_read_b128 v[212:215], v228 offset:16384
	ds_read_b128 v[216:219], v228 offset:17408
	ds_read_b128 v[220:223], v228 offset:18432
	ds_read_b128 v[224:227], v228 offset:19456
	s_mov_b32 m0, s69
	s_nop 0
	global_load_lds_dwordx4 v132, s[56:57]
	s_add_i32 m0, s69, 0x2000
	s_nop 0
	global_load_lds_dwordx4 v138, s[56:57]
	s_barrier
	s_waitcnt lgkmcnt(0)
	s_setprio 0
	v_mfma_f32_16x16x32_bf16 v[112:115], v[212:215], v[180:183], v[112:115]
	v_mfma_f32_16x16x32_bf16 v[108:111], v[220:223], v[180:183], v[108:111]
	v_mfma_f32_16x16x32_bf16 v[96:99], v[212:215], v[188:191], v[96:99]
	v_mfma_f32_16x16x32_bf16 v[92:95], v[220:223], v[188:191], v[92:95]
	v_mfma_f32_16x16x32_bf16 v[80:83], v[212:215], v[196:199], v[80:83]
	v_mfma_f32_16x16x32_bf16 v[76:79], v[220:223], v[196:199], v[76:79]
	v_mfma_f32_16x16x32_bf16 v[72:75], v[212:215], v[204:207], v[72:75]
	v_mfma_f32_16x16x32_bf16 v[68:71], v[220:223], v[204:207], v[68:71]
	v_mfma_f32_16x16x32_bf16 v[112:115], v[216:219], v[184:187], v[112:115]
	v_mfma_f32_16x16x32_bf16 v[108:111], v[224:227], v[184:187], v[108:111]
	v_mfma_f32_16x16x32_bf16 v[96:99], v[216:219], v[192:195], v[96:99]
	v_mfma_f32_16x16x32_bf16 v[92:95], v[224:227], v[192:195], v[92:95]
	v_mfma_f32_16x16x32_bf16 v[80:83], v[216:219], v[200:203], v[80:83]
	v_mfma_f32_16x16x32_bf16 v[76:79], v[224:227], v[200:203], v[76:79]
	v_mfma_f32_16x16x32_bf16 v[72:75], v[216:219], v[208:211], v[72:75]
	v_mfma_f32_16x16x32_bf16 v[68:71], v[224:227], v[208:211], v[68:71]
	s_setprio 2
	s_mov_b32 m0, s52
	s_barrier
	ds_read_b128 v[180:183], v146 offset:16384
	ds_read_b128 v[184:187], v146 offset:17408
	ds_read_b128 v[188:191], v146 offset:18432
	ds_read_b128 v[192:195], v146 offset:19456
	ds_read_b128 v[196:199], v146 offset:20480
	ds_read_b128 v[200:203], v146 offset:21504
	ds_read_b128 v[204:207], v146 offset:22528
	ds_read_b128 v[208:211], v146 offset:23552
	global_load_lds_dwordx4 v132, s[4:5]
	s_mov_b32 m0, s53
	s_nop 0
	global_load_lds_dwordx4 v138, s[4:5]
	s_barrier
	s_waitcnt lgkmcnt(0)
	s_setprio 0
	v_mfma_f32_16x16x32_bf16 v[64:67], v[148:151], v[180:183], v[64:67]
	v_mfma_f32_16x16x32_bf16 v[60:63], v[156:159], v[180:183], v[60:63]
	v_mfma_f32_16x16x32_bf16 v[56:59], v[148:151], v[188:191], v[56:59]
	v_mfma_f32_16x16x32_bf16 v[52:55], v[156:159], v[188:191], v[52:55]
	v_mfma_f32_16x16x32_bf16 v[40:43], v[148:151], v[196:199], v[40:43]
	v_mfma_f32_16x16x32_bf16 v[36:39], v[156:159], v[196:199], v[36:39]
	v_mfma_f32_16x16x32_bf16 v[24:27], v[148:151], v[204:207], v[24:27]
	v_mfma_f32_16x16x32_bf16 v[20:23], v[156:159], v[204:207], v[20:23]
	v_mfma_f32_16x16x32_bf16 v[64:67], v[152:155], v[184:187], v[64:67]
	v_mfma_f32_16x16x32_bf16 v[60:63], v[176:179], v[184:187], v[60:63]
	v_mfma_f32_16x16x32_bf16 v[56:59], v[152:155], v[192:195], v[56:59]
	v_mfma_f32_16x16x32_bf16 v[52:55], v[176:179], v[192:195], v[52:55]
	v_mfma_f32_16x16x32_bf16 v[40:43], v[152:155], v[200:203], v[40:43]
	v_mfma_f32_16x16x32_bf16 v[36:39], v[176:179], v[200:203], v[36:39]
	s_setprio 3
	s_barrier
	v_mfma_f32_16x16x32_bf16 v[24:27], v[152:155], v[208:211], v[24:27]
	v_mfma_f32_16x16x32_bf16 v[20:23], v[176:179], v[208:211], v[20:23]
	s_setprio 2
	s_add_u32 s70, s56, 0x4000
	s_addc_u32 s71, s57, 0
	s_add_i32 s69, s72, s39
	s_mov_b32 m0, s69
	s_nop 0
	global_load_lds_dwordx4 v132, s[70:71]
	s_add_i32 m0, s69, 0x2000
	s_nop 0
	global_load_lds_dwordx4 v138, s[70:71]
	s_waitcnt vmcnt(6)
	s_barrier
; #define PG8_STAGE(bufoff, gbase, voff) do { _Pragma("unroll") for (int _i = 0; _i < 2; ++_i) \
;         __builtin_amdgcn_global_load_lds((const unsigned*)((const char*)(gbase) + (voff)[_i]), (LAS unsigned*)(lds + (bufoff) + ldsw + _i * 8192), 16, 0, 0); } while (0)
; #define PG8_LDA(dst, b, h) do { _Pragma("unroll") for (int m = 0; m < 4; ++m) _Pragma("unroll") for (int k = 0; k < 2; ++k) dst[m][k] = *(const LAS bf16x8*)(lds + PG8_SA(b, h) + aoff + m * 2048 + k * 1024); } while (0)
; #define PG8_LDB(dst, b, h) do { _Pragma("unroll") for (int n = 0; n < 2; ++n) _Pragma("unroll") for (int k = 0; k < 2; ++k) dst[n][k] = *(const LAS bf16x8*)(lds + PG8_SB(b, h) + boff + n * 2048 + k * 1024); } while (0)
; #define PG8_MMA(ai, bj, At, Bt) do { __builtin_amdgcn_s_setprio(1); _Pragma("unroll") for (int m = 0; m < 4; ++m) _Pragma("unroll") for (int n = 0; n < 2; ++n) _Pragma("unroll") for (int k = 0; k < 2; ++k) \
;         acc[ai][bj][m][n] = __builtin_amdgcn_mfma_f32_16x16x32_bf16(Bt[n][k], At[m][k], acc[ai][bj][m][n], 0, 0, 0); __builtin_amdgcn_s_setprio(0); } while (0)
; #define PG8_WAIT_V(n) asm volatile("s_waitcnt vmcnt(" #n ")" ::: "memory")
; #define PG8_WAIT_L(n) asm volatile("s_waitcnt lgkmcnt(" #n ")" ::: "memory")
; #define PG8_BAR __builtin_amdgcn_s_barrier()
; #define PG8_SCHED __builtin_amdgcn_sched_barrier(0)
; template <class Epi, class Sched, int LD>
; __device__ __forceinline__ void gemm_phase(LAS unsigned char* lds, const Gemm g, const Sched& S, const Epi& E) {
;     ...
;             PG8_WAIT_V(6); PG8_BAR; PG8_MMA(1, 1, At, B1); PG8_BAR;
;             PG8_LDB(B0, 1, 0); PG8_SCHED; PG8_LDA(At, 1, 0); PG8_STAGE(PG8_SA(0, 1), a2 + hstep, voffA);
;             PG8_WAIT_L(8); PG8_BAR; PG8_WAIT_L(0); PG8_MMA(0, 0, At, B0); PG8_BAR; PG8_SCHED;
;             PG8_LDB(B1, 1, 1); PG8_STAGE(PG8_SB(1, 0), b3, voffB);
;             PG8_BAR; PG8_WAIT_L(0); PG8_MMA(0, 1, At, B1); PG8_BAR;
	s_setprio 0
	v_mfma_f32_16x16x32_bf16 v[48:51], v[212:215], v[180:183], v[48:51]
	v_mfma_f32_16x16x32_bf16 v[44:47], v[220:223], v[180:183], v[44:47]
	v_mfma_f32_16x16x32_bf16 v[32:35], v[212:215], v[188:191], v[32:35]
	v_mfma_f32_16x16x32_bf16 v[28:31], v[220:223], v[188:191], v[28:31]
	v_mfma_f32_16x16x32_bf16 v[16:19], v[212:215], v[196:199], v[16:19]
	v_mfma_f32_16x16x32_bf16 v[12:15], v[220:223], v[196:199], v[12:15]
	v_mfma_f32_16x16x32_bf16 v[8:11], v[212:215], v[204:207], v[8:11]
	v_mfma_f32_16x16x32_bf16 v[4:7], v[220:223], v[204:207], v[4:7]
	v_mfma_f32_16x16x32_bf16 v[48:51], v[216:219], v[184:187], v[48:51]
	v_mfma_f32_16x16x32_bf16 v[44:47], v[224:227], v[184:187], v[44:47]
	v_mfma_f32_16x16x32_bf16 v[32:35], v[216:219], v[192:195], v[32:35]
	v_mfma_f32_16x16x32_bf16 v[28:31], v[224:227], v[192:195], v[28:31]
	v_mfma_f32_16x16x32_bf16 v[16:19], v[216:219], v[200:203], v[16:19]
	v_mfma_f32_16x16x32_bf16 v[12:15], v[224:227], v[200:203], v[12:15]
	v_mfma_f32_16x16x32_bf16 v[8:11], v[216:219], v[208:211], v[8:11]
	v_mfma_f32_16x16x32_bf16 v[4:7], v[224:227], v[208:211], v[4:7]
	s_setprio 2
	s_add_i32 s69, 0, 0x18000
	s_barrier
	ds_read_b128 v[148:151], v228 offset:32768
	ds_read_b128 v[152:155], v228 offset:33792
	ds_read_b128 v[156:159], v228 offset:34816
	ds_read_b128 v[176:179], v228 offset:35840
	s_add_u32 s4, s4, 0x4000
	s_addc_u32 s5, s5, 0
	s_mov_b32 m0, s60
	ds_read_b128 v[180:183], v146 offset:32768
	ds_read_b128 v[184:187], v146 offset:33792
	ds_read_b128 v[188:191], v146 offset:34816
	ds_read_b128 v[192:195], v146 offset:35840
	ds_read_b128 v[196:199], v146 offset:36864
	ds_read_b128 v[200:203], v146 offset:37888
	ds_read_b128 v[204:207], v146 offset:38912
	ds_read_b128 v[208:211], v146 offset:39936
	global_load_lds_dwordx4 v132, s[4:5]
	s_mov_b32 m0, s61
	s_nop 0
	global_load_lds_dwordx4 v138, s[4:5]
	s_waitcnt lgkmcnt(8)
	s_barrier
	s_waitcnt lgkmcnt(0)
	s_setprio 0
	v_mfma_f32_16x16x32_bf16 v[128:131], v[148:151], v[180:183], v[128:131]
	v_mfma_f32_16x16x32_bf16 v[124:127], v[156:159], v[180:183], v[124:127]
	v_mfma_f32_16x16x32_bf16 v[120:123], v[148:151], v[188:191], v[120:123]
	v_mfma_f32_16x16x32_bf16 v[116:119], v[156:159], v[188:191], v[116:119]
	v_mfma_f32_16x16x32_bf16 v[104:107], v[148:151], v[196:199], v[104:107]
	v_mfma_f32_16x16x32_bf16 v[100:103], v[156:159], v[196:199], v[100:103]
	v_mfma_f32_16x16x32_bf16 v[88:91], v[148:151], v[204:207], v[88:91]
	v_mfma_f32_16x16x32_bf16 v[84:87], v[156:159], v[204:207], v[84:87]
	v_mfma_f32_16x16x32_bf16 v[128:131], v[152:155], v[184:187], v[128:131]
	v_mfma_f32_16x16x32_bf16 v[124:127], v[176:179], v[184:187], v[124:127]
	v_mfma_f32_16x16x32_bf16 v[120:123], v[152:155], v[192:195], v[120:123]
	v_mfma_f32_16x16x32_bf16 v[116:119], v[176:179], v[192:195], v[116:119]
	v_mfma_f32_16x16x32_bf16 v[104:107], v[152:155], v[200:203], v[104:107]
	v_mfma_f32_16x16x32_bf16 v[100:103], v[176:179], v[200:203], v[100:103]
	s_setprio 3
	s_barrier
	v_mfma_f32_16x16x32_bf16 v[88:91], v[152:155], v[208:211], v[88:91]
	v_mfma_f32_16x16x32_bf16 v[84:87], v[176:179], v[208:211], v[84:87]
	s_setprio 2
	s_add_i32 s70, 0, 0x1c000
	s_add_u32 s4, s56, 0x8000
	s_addc_u32 s5, s57, 0
	s_add_i32 s69, s69, s39
	ds_read_b128 v[212:215], v228 offset:49152
	ds_read_b128 v[216:219], v228 offset:50176
	ds_read_b128 v[220:223], v228 offset:51200
	ds_read_b128 v[224:227], v228 offset:52224
	s_mov_b32 m0, s69
	s_nop 0
	global_load_lds_dwordx4 v132, s[4:5]
	s_add_i32 m0, s69, 0x2000
	s_nop 0
	global_load_lds_dwordx4 v138, s[4:5]
	s_barrier
	s_waitcnt lgkmcnt(0)
	s_setprio 0
	v_mfma_f32_16x16x32_bf16 v[112:115], v[212:215], v[180:183], v[112:115]
	v_mfma_f32_16x16x32_bf16 v[108:111], v[220:223], v[180:183], v[108:111]
	v_mfma_f32_16x16x32_bf16 v[96:99], v[212:215], v[188:191], v[96:99]
	v_mfma_f32_16x16x32_bf16 v[92:95], v[220:223], v[188:191], v[92:95]
	v_mfma_f32_16x16x32_bf16 v[80:83], v[212:215], v[196:199], v[80:83]
	v_mfma_f32_16x16x32_bf16 v[76:79], v[220:223], v[196:199], v[76:79]
	v_mfma_f32_16x16x32_bf16 v[72:75], v[212:215], v[204:207], v[72:75]
	v_mfma_f32_16x16x32_bf16 v[68:71], v[220:223], v[204:207], v[68:71]
	v_mfma_f32_16x16x32_bf16 v[112:115], v[216:219], v[184:187], v[112:115]
	v_mfma_f32_16x16x32_bf16 v[108:111], v[224:227], v[184:187], v[108:111]
	v_mfma_f32_16x16x32_bf16 v[96:99], v[216:219], v[192:195], v[96:99]
	v_mfma_f32_16x16x32_bf16 v[92:95], v[224:227], v[192:195], v[92:95]
	v_mfma_f32_16x16x32_bf16 v[80:83], v[216:219], v[200:203], v[80:83]
	v_mfma_f32_16x16x32_bf16 v[76:79], v[224:227], v[200:203], v[76:79]
	v_mfma_f32_16x16x32_bf16 v[72:75], v[216:219], v[208:211], v[72:75]
	v_mfma_f32_16x16x32_bf16 v[68:71], v[224:227], v[208:211], v[68:71]
	s_setprio 2
	s_mov_b32 m0, s64
	s_barrier
	ds_read_b128 v[180:183], v146 offset:49152
	ds_read_b128 v[184:187], v146 offset:50176
	ds_read_b128 v[188:191], v146 offset:51200
	ds_read_b128 v[192:195], v146 offset:52224
	ds_read_b128 v[196:199], v146 offset:53248
	ds_read_b128 v[200:203], v146 offset:54272
	ds_read_b128 v[204:207], v146 offset:55296
	ds_read_b128 v[208:211], v146 offset:56320
	global_load_lds_dwordx4 v132, s[58:59]
	s_mov_b32 m0, s65
	s_nop 0
	global_load_lds_dwordx4 v138, s[58:59]
	s_barrier
; #define PG8_STAGE(bufoff, gbase, voff) do { _Pragma("unroll") for (int _i = 0; _i < 2; ++_i) \
;         __builtin_amdgcn_global_load_lds((const unsigned*)((const char*)(gbase) + (voff)[_i]), (LAS unsigned*)(lds + (bufoff) + ldsw + _i * 8192), 16, 0, 0); } while (0)
; #define PG8_MMA(ai, bj, At, Bt) do { __builtin_amdgcn_s_setprio(1); _Pragma("unroll") for (int m = 0; m < 4; ++m) _Pragma("unroll") for (int n = 0; n < 2; ++n) _Pragma("unroll") for (int k = 0; k < 2; ++k) \
;         acc[ai][bj][m][n] = __builtin_amdgcn_mfma_f32_16x16x32_bf16(Bt[n][k], At[m][k], acc[ai][bj][m][n], 0, 0, 0); __builtin_amdgcn_s_setprio(0); } while (0)
; #define PG8_WAIT_V(n) asm volatile("s_waitcnt vmcnt(" #n ")" ::: "memory")
; #define PG8_WAIT_L(n) asm volatile("s_waitcnt lgkmcnt(" #n ")" ::: "memory")
; #define PG8_BAR __builtin_amdgcn_s_barrier()
; #define PG8_SCHED __builtin_amdgcn_sched_barrier(0)
;     __device__ __forceinline__ void operator()(const f32x4 (&acc)[2][2][4][2], const Unit& u, int wr, int wc, int fr, int fq) const {
;     ...
;         } else if (wc == 0) {
; #pragma unroll
;             for (int ai = 0; ai < 2; ++ai)
; #pragma unroll
;                 for (int m = 0; m < 4; ++m) {
;                     float* rowp = DT + (size_t)(row0 + ai * HALF + m * 16) * 32 + 8 * fq;
;                     *(f32x4*)rowp = acc[ai][0][m][0]; *(f32x4*)(rowp + 4) = acc[ai][0][m][1];
;                 }
; template <class Epi, class Sched, int LD>
; __device__ __forceinline__ void gemm_phase(LAS unsigned char* lds, const Gemm g, const Sched& S, const Epi& E) {
;     ...
;             PG8_BAR; PG8_WAIT_L(0); PG8_MMA(1, 0, At, B0); PG8_BAR; PG8_SCHED;
;             PG8_STAGE(PG8_SB(1, 1), b3 + hstep, voffB);
;             PG8_WAIT_V(6); PG8_BAR; PG8_MMA(1, 1, At, B1); PG8_BAR;
	s_waitcnt lgkmcnt(0)
	s_setprio 0
	v_mfma_f32_16x16x32_bf16 v[64:67], v[148:151], v[180:183], v[64:67]
	v_mfma_f32_16x16x32_bf16 v[60:63], v[156:159], v[180:183], v[60:63]
	v_mfma_f32_16x16x32_bf16 v[56:59], v[148:151], v[188:191], v[56:59]
	v_mfma_f32_16x16x32_bf16 v[52:55], v[156:159], v[188:191], v[52:55]
	v_mfma_f32_16x16x32_bf16 v[40:43], v[148:151], v[196:199], v[40:43]
	v_mfma_f32_16x16x32_bf16 v[36:39], v[156:159], v[196:199], v[36:39]
	v_mfma_f32_16x16x32_bf16 v[24:27], v[148:151], v[204:207], v[24:27]
	v_mfma_f32_16x16x32_bf16 v[20:23], v[156:159], v[204:207], v[20:23]
	v_mfma_f32_16x16x32_bf16 v[64:67], v[152:155], v[184:187], v[64:67]
	v_mfma_f32_16x16x32_bf16 v[60:63], v[176:179], v[184:187], v[60:63]
	v_mfma_f32_16x16x32_bf16 v[56:59], v[152:155], v[192:195], v[56:59]
	v_mfma_f32_16x16x32_bf16 v[52:55], v[176:179], v[192:195], v[52:55]
	v_mfma_f32_16x16x32_bf16 v[40:43], v[152:155], v[200:203], v[40:43]
	v_mfma_f32_16x16x32_bf16 v[36:39], v[176:179], v[200:203], v[36:39]
	s_setprio 3
	s_barrier
	v_mfma_f32_16x16x32_bf16 v[24:27], v[152:155], v[208:211], v[24:27]
	v_mfma_f32_16x16x32_bf16 v[20:23], v[176:179], v[208:211], v[20:23]
	s_setprio 2
	s_add_u32 s4, s56, 0xc000
	s_addc_u32 s5, s57, 0
	s_add_i32 s56, s70, s39
	s_mov_b32 m0, s56
	s_nop 0
	global_load_lds_dwordx4 v132, s[4:5]
	s_add_i32 m0, s56, 0x2000
	s_nop 0
	global_load_lds_dwordx4 v138, s[4:5]
	s_waitcnt vmcnt(6)
	s_barrier
	s_setprio 0
	v_mfma_f32_16x16x32_bf16 v[48:51], v[212:215], v[180:183], v[48:51]
	v_mfma_f32_16x16x32_bf16 v[44:47], v[220:223], v[180:183], v[44:47]
	v_mfma_f32_16x16x32_bf16 v[32:35], v[212:215], v[188:191], v[32:35]
	v_mfma_f32_16x16x32_bf16 v[28:31], v[220:223], v[188:191], v[28:31]
	v_mfma_f32_16x16x32_bf16 v[16:19], v[212:215], v[196:199], v[16:19]
	v_mfma_f32_16x16x32_bf16 v[12:15], v[220:223], v[196:199], v[12:15]
	v_mfma_f32_16x16x32_bf16 v[8:11], v[212:215], v[204:207], v[8:11]
	v_mfma_f32_16x16x32_bf16 v[4:7], v[220:223], v[204:207], v[4:7]
	v_mfma_f32_16x16x32_bf16 v[48:51], v[216:219], v[184:187], v[48:51]
	v_mfma_f32_16x16x32_bf16 v[44:47], v[224:227], v[184:187], v[44:47]
	v_mfma_f32_16x16x32_bf16 v[32:35], v[216:219], v[192:195], v[32:35]
	v_mfma_f32_16x16x32_bf16 v[28:31], v[224:227], v[192:195], v[28:31]
	v_mfma_f32_16x16x32_bf16 v[16:19], v[216:219], v[200:203], v[16:19]
	v_mfma_f32_16x16x32_bf16 v[12:15], v[224:227], v[200:203], v[12:15]
	v_mfma_f32_16x16x32_bf16 v[8:11], v[216:219], v[208:211], v[8:11]
	v_mfma_f32_16x16x32_bf16 v[4:7], v[224:227], v[208:211], v[4:7]
	s_setprio 2
	s_add_i32 s49, s49, 2
	s_add_u32 s54, s54, 0x10000
	s_addc_u32 s55, s55, 0
	s_add_u32 s29, s29, 0x10000
	s_addc_u32 s47, s47, 0
	s_cmp_gt_u32 s49, 29
	s_barrier
	s_cbranch_scc0 .LBB0_501
	s_setprio 0
	v_lshl_add_u32 v142, s68, 8, v137
	s_cmp_gt_i32 s67, 35
	s_mov_b64 s[4:5], -1
	s_cbranch_scc0 .LBB0_506
	s_andn2_b64 vcc, exec, s[42:43]
	s_cbranch_vccnz .LBB0_505
	v_or_b32_e32 v150, 16, v142
	v_ashrrev_i32_e32 v143, 31, v142
	v_ashrrev_i32_e32 v151, 31, v150
	v_lshlrev_b64 v[148:149], 7, v[142:143]
	v_lshlrev_b64 v[150:151], 7, v[150:151]
	v_lshl_add_u64 v[148:149], v[140:141], 0, v[148:149]
	v_lshl_add_u64 v[150:151], v[140:141], 0, v[150:151]
	global_store_dwordx4 v[148:149], v[128:131], off
	global_store_dwordx4 v[148:149], v[124:127], off offset:16
	global_store_dwordx4 v[150:151], v[120:123], off
	global_store_dwordx4 v[150:151], v[116:119], off offset:16
	v_or_b32_e32 v150, 32, v142
	v_ashrrev_i32_e32 v151, 31, v150
	v_lshlrev_b64 v[150:151], 7, v[150:151]
	v_lshl_add_u64 v[150:151], v[140:141], 0, v[150:151]
	global_store_dwordx4 v[150:151], v[104:107], off
	global_store_dwordx4 v[150:151], v[100:103], off offset:16
	v_or_b32_e32 v150, 48, v142
	v_ashrrev_i32_e32 v151, 31, v150
	v_lshlrev_b64 v[150:151], 7, v[150:151]
	v_lshl_add_u64 v[150:151], v[140:141], 0, v[150:151]
	s_mov_b64 s[4:5], 0x4000
	global_store_dwordx4 v[150:151], v[88:91], off
	global_store_dwordx4 v[150:151], v[84:87], off offset:16
	v_lshl_add_u64 v[150:151], v[148:149], 0, s[4:5]
	s_movk_i32 s4, 0x4000
	v_add_co_u32_e32 v152, vcc, s4, v148
	s_mov_b64 s[4:5], 0x4800
	s_nop 0
	v_addc_co_u32_e32 v153, vcc, 0, v149, vcc
	global_store_dwordx4 v[152:153], v[64:67], off
	global_store_dwordx4 v[150:151], v[60:63], off offset:16
	v_lshl_add_u64 v[150:151], v[148:149], 0, s[4:5]
	global_store_dwordx4 v[152:153], v[56:59], off offset:2048
	global_store_dwordx4 v[150:151], v[52:55], off offset:16
	s_mov_b64 s[4:5], 0x5000
	v_add_co_u32_e32 v152, vcc, 0x5000, v148
	v_lshl_add_u64 v[150:151], v[148:149], 0, s[4:5]
	s_nop 0
	v_addc_co_u32_e32 v153, vcc, 0, v149, vcc
	s_mov_b64 s[4:5], 0x5800
	global_store_dwordx4 v[152:153], v[40:43], off
	global_store_dwordx4 v[150:151], v[36:39], off offset:16
	v_lshl_add_u64 v[148:149], v[148:149], 0, s[4:5]
	global_store_dwordx4 v[152:153], v[24:27], off offset:2048
	global_store_dwordx4 v[148:149], v[20:23], off offset:16

; template <int MODE>
; __device__ __forceinline__ void norm_row(const Params& p, const f32x4 (&g)[8], int r, int lane, int nparts, float pscale) {
;     ...
;         for (int k = 0; k < nparts; ++k) {
; #pragma unroll
;             for (int i = 0; i < 8; ++i) a[i] += *(const f32x4*)(pp + (size_t)k * (512 * 2048) + i * 256);
;         }
.LBB0_722:
	s_andn2_b64 vcc, exec, s[4:5]
	s_cbranch_vccz .LBB0_718
	s_waitcnt vmcnt(0)
.LBB0_723:
	v_lshl_add_u64 v[88:89], v[86:87], 0, s[44:45]
	v_add_co_u32_e32 v94, vcc, s37, v88
	s_mov_b64 s[4:5], -1
	s_nop 0
	v_addc_co_u32_e32 v95, vcc, 0, v89, vcc
	v_add_co_u32_e32 v96, vcc, s62, v88
	s_cmp_eq_u32 s44, 0x2000000
	s_nop 0
	v_addc_co_u32_e32 v97, vcc, 0, v89, vcc
	global_load_dwordx4 v[200:203], v[96:97], off offset:-4096
	global_load_dwordx4 v[204:207], v[94:95], off offset:1024
	global_load_dwordx4 v[208:211], v[94:95], off offset:2048
	global_load_dwordx4 v[212:215], v[94:95], off offset:3072
	global_load_dwordx4 v[216:219], v[96:97], off
	global_load_dwordx4 v[220:223], v[96:97], off offset:1024
	global_load_dwordx4 v[224:227], v[96:97], off offset:2048
	global_load_dwordx4 v[228:231], v[96:97], off offset:3072
	s_waitcnt vmcnt(0)
	v_pk_add_f32 v[98:99], v[158:159], v[202:203]
	v_pk_add_f32 v[100:101], v[156:157], v[200:201]
	v_pk_add_f32 v[102:103], v[154:155], v[206:207]
	v_pk_add_f32 v[104:105], v[152:153], v[204:205]
	v_pk_add_f32 v[106:107], v[150:151], v[210:211]
	v_pk_add_f32 v[108:109], v[148:149], v[208:209]
	v_pk_add_f32 v[94:95], v[146:147], v[214:215]
	v_pk_add_f32 v[110:111], v[144:145], v[212:213]
	v_pk_add_f32 v[112:113], v[142:143], v[218:219]
	v_pk_add_f32 v[114:115], v[140:141], v[216:217]
	v_pk_add_f32 v[116:117], v[138:139], v[222:223]
	v_pk_add_f32 v[118:119], v[130:131], v[220:221]
	v_pk_add_f32 v[120:121], v[128:129], v[226:227]
	v_pk_add_f32 v[126:127], v[126:127], v[224:225]
	v_pk_add_f32 v[96:97], v[124:125], v[230:231]
	v_add_co_u32_e32 v124, vcc, s63, v88
	s_nop 0
	v_addc_co_u32_e32 v125, vcc, 0, v89, vcc
	v_add_co_u32_e32 v128, vcc, s26, v88
	s_nop 1
	v_addc_co_u32_e32 v129, vcc, 0, v89, vcc
	global_load_dwordx4 v[232:235], v[128:129], off offset:-4096
	global_load_dwordx4 v[236:239], v[124:125], off offset:1024
	global_load_dwordx4 v[240:243], v[124:125], off offset:2048
	global_load_dwordx4 v[244:247], v[124:125], off offset:3072
	global_load_dwordx4 v[200:203], v[128:129], off
	global_load_dwordx4 v[204:207], v[128:129], off offset:1024
	global_load_dwordx4 v[208:211], v[128:129], off offset:2048
	global_load_dwordx4 v[212:215], v[128:129], off offset:3072
	v_add_co_u32_e32 v128, vcc, s30, v88
	v_addc_co_u32_e32 v129, vcc, 0, v89, vcc
	v_add_co_u32_e32 v138, vcc, s31, v88
	s_nop 0
	v_addc_co_u32_e32 v139, vcc, 0, v89, vcc
	global_load_dwordx4 v[216:219], v[138:139], off offset:-4096
	global_load_dwordx4 v[220:223], v[128:129], off offset:1024
	global_load_dwordx4 v[224:227], v[128:129], off offset:2048
	s_waitcnt vmcnt(0)
	v_pk_add_f32 v[122:123], v[122:123], v[228:229]
	v_pk_add_f32 v[98:99], v[98:99], v[234:235]
	v_pk_add_f32 v[100:101], v[100:101], v[232:233]
	v_pk_add_f32 v[102:103], v[102:103], v[238:239]
	v_pk_add_f32 v[104:105], v[104:105], v[236:237]
	v_pk_add_f32 v[106:107], v[106:107], v[242:243]
	v_pk_add_f32 v[108:109], v[108:109], v[240:241]
	v_pk_add_f32 v[124:125], v[94:95], v[246:247]
	v_pk_add_f32 v[110:111], v[110:111], v[244:245]
	v_pk_add_f32 v[112:113], v[112:113], v[202:203]
	v_pk_add_f32 v[114:115], v[114:115], v[200:201]
	v_pk_add_f32 v[116:117], v[116:117], v[206:207]
	v_pk_add_f32 v[130:131], v[118:119], v[204:205]
	v_pk_add_f32 v[120:121], v[120:121], v[210:211]
	v_pk_add_f32 v[126:127], v[126:127], v[208:209]
	v_pk_add_f32 v[118:119], v[96:97], v[214:215]
	v_pk_add_f32 v[122:123], v[122:123], v[212:213]
	v_pk_add_f32 v[92:93], v[98:99], v[218:219]
	v_pk_add_f32 v[90:91], v[100:101], v[216:217]
	v_pk_add_f32 v[96:97], v[102:103], v[222:223]
	v_pk_add_f32 v[94:95], v[104:105], v[220:221]
	global_load_dwordx4 v[228:231], v[128:129], off offset:3072
	global_load_dwordx4 v[232:235], v[138:139], off
	global_load_dwordx4 v[236:239], v[138:139], off offset:1024
	global_load_dwordx4 v[240:243], v[138:139], off offset:2048
	global_load_dwordx4 v[244:247], v[138:139], off offset:3072
	s_waitcnt vmcnt(0)
	v_pk_add_f32 v[100:101], v[106:107], v[226:227]
	v_pk_add_f32 v[98:99], v[108:109], v[224:225]
	v_pk_add_f32 v[102:103], v[110:111], v[228:229]
	v_pk_add_f32 v[104:105], v[124:125], v[230:231]
	v_pk_add_f32 v[108:109], v[112:113], v[234:235]
	v_pk_add_f32 v[106:107], v[114:115], v[232:233]
	v_pk_add_f32 v[112:113], v[116:117], v[238:239]
	v_pk_add_f32 v[110:111], v[130:131], v[236:237]
	v_pk_add_f32 v[114:115], v[126:127], v[240:241]
	v_pk_add_f32 v[116:117], v[120:121], v[242:243]
	v_pk_add_f32 v[120:121], v[118:119], v[246:247]
	v_pk_add_f32 v[118:119], v[122:123], v[244:245]
	s_waitcnt vmcnt(0)
	v_mov_b32_e32 v124, v244
	v_mov_b32_e32 v125, v245
	v_mov_b32_e32 v126, v246
	v_mov_b32_e32 v127, v247
	s_cbranch_scc1 .LBB0_722
	s_mov_b32 s2, 0x2a801000
	v_add_co_u32_e32 v130, vcc, s2, v88
	s_add_u32 s44, s44, 0x1000000
	s_nop 0
	v_addc_co_u32_e32 v131, vcc, 0, v89, vcc
	v_add_co_u32_e32 v88, vcc, 0x2a800000, v88
	global_load_dwordx4 v[200:203], v[130:131], off
	s_nop 0
	v_addc_co_u32_e32 v89, vcc, 0, v89, vcc
	global_load_dwordx4 v[204:207], v[130:131], off offset:1024
	global_load_dwordx4 v[208:211], v[130:131], off offset:2048
	global_load_dwordx4 v[212:215], v[130:131], off offset:3072
	global_load_dwordx4 v[216:219], v[88:89], off
	global_load_dwordx4 v[220:223], v[88:89], off offset:1024
	global_load_dwordx4 v[224:227], v[88:89], off offset:2048
	global_load_dwordx4 v[228:231], v[88:89], off offset:3072
	s_addc_u32 s45, s45, 0
	s_mov_b64 s[4:5], 0
	s_waitcnt vmcnt(0)
	v_pk_add_f32 v[142:143], v[108:109], v[202:203]
	v_pk_add_f32 v[140:141], v[106:107], v[200:201]
	v_pk_add_f32 v[138:139], v[112:113], v[206:207]
	v_pk_add_f32 v[130:131], v[110:111], v[204:205]
	v_pk_add_f32 v[128:129], v[116:117], v[210:211]
	v_pk_add_f32 v[126:127], v[114:115], v[208:209]
	v_pk_add_f32 v[124:125], v[120:121], v[214:215]
	v_pk_add_f32 v[122:123], v[118:119], v[212:213]
	v_pk_add_f32 v[158:159], v[92:93], v[218:219]
	v_pk_add_f32 v[156:157], v[90:91], v[216:217]
	v_pk_add_f32 v[154:155], v[96:97], v[222:223]
	v_pk_add_f32 v[152:153], v[94:95], v[220:221]
	v_pk_add_f32 v[150:151], v[100:101], v[226:227]
	v_pk_add_f32 v[148:149], v[98:99], v[224:225]
	v_pk_add_f32 v[146:147], v[104:105], v[230:231]
	v_pk_add_f32 v[144:145], v[102:103], v[228:229]
	s_waitcnt vmcnt(0)
	v_mov_b32_e32 v188, v220
	v_mov_b32_e32 v189, v221
	v_mov_b32_e32 v190, v222
	v_mov_b32_e32 v191, v223
	v_mov_b32_e32 v192, v224
	v_mov_b32_e32 v193, v225
	v_mov_b32_e32 v194, v226
	v_mov_b32_e32 v195, v227
	v_mov_b32_e32 v196, v228
	v_mov_b32_e32 v197, v229
	v_mov_b32_e32 v198, v230
	v_mov_b32_e32 v199, v231
	s_branch .LBB0_722

; template <int MODE>
; __device__ __forceinline__ void norm_row(const Params& p, const f32x4 (&g)[8], int r, int lane, int nparts, float pscale) {
;     ...
;     for (int i = 0; i < 8; ++i) v[i] = *(const f32x4*)(src + i * 256 + lane * 4);
;     if (MODE != 0 && nparts > 0 && r >= 8192) {
;         const float* pp = (const float*)(p.ws + WS_ST) + (size_t)(r - 8192) * 2048 + lane * 4;
;         f32x4 a[8];
; #pragma unroll
;         for (int i = 0; i < 8; ++i) a[i] = (f32x4){0.f, 0.f, 0.f, 0.f};
;         for (int k = 0; k < nparts; ++k) {
; #pragma unroll
;             for (int i = 0; i < 8; ++i) a[i] += *(const f32x4*)(pp + (size_t)k * (512 * 2048) + i * 256);
.LBB0_737:
	s_waitcnt vmcnt(0)
	v_add_u32_e32 v78, 0x2000, v72
	v_ashrrev_i32_e32 v79, 31, v78
	v_lshlrev_b64 v[36:37], 13, v[78:79]
	v_lshl_add_u64 v[82:83], v[74:75], 0, v[36:37]
	v_add_co_u32_e32 v36, vcc, 0x1000, v82
	global_load_dwordx4 v[200:203], v[82:83], off
	global_load_dwordx4 v[204:207], v[82:83], off offset:1024
	global_load_dwordx4 v[208:211], v[82:83], off offset:2048
	global_load_dwordx4 v[212:215], v[82:83], off offset:3072
	v_addc_co_u32_e32 v37, vcc, 0, v83, vcc
	global_load_dwordx4 v[216:219], v[36:37], off
	global_load_dwordx4 v[220:223], v[36:37], off offset:1024
	global_load_dwordx4 v[224:227], v[36:37], off offset:2048
	s_nop 0
	global_load_dwordx4 v[228:231], v[36:37], off offset:3072
	s_waitcnt vmcnt(0)
	v_mov_b32_e32 v36, v228
	v_mov_b32_e32 v37, v229
	v_mov_b32_e32 v38, v230
	v_mov_b32_e32 v39, v231
	v_mov_b32_e32 v40, v224
	v_mov_b32_e32 v41, v225
	v_mov_b32_e32 v42, v226
	v_mov_b32_e32 v43, v227
	v_mov_b32_e32 v44, v220
	v_mov_b32_e32 v45, v221
	v_mov_b32_e32 v46, v222
	v_mov_b32_e32 v47, v223
	v_mov_b32_e32 v48, v216
	v_mov_b32_e32 v49, v217
	v_mov_b32_e32 v50, v218
	v_mov_b32_e32 v51, v219
	v_mov_b32_e32 v52, v212
	v_mov_b32_e32 v53, v213
	v_mov_b32_e32 v54, v214
	v_mov_b32_e32 v55, v215
	v_mov_b32_e32 v56, v208
	v_mov_b32_e32 v57, v209
	v_mov_b32_e32 v58, v210
	v_mov_b32_e32 v59, v211
	v_mov_b32_e32 v60, v204
	v_mov_b32_e32 v61, v205
	v_mov_b32_e32 v62, v206
	v_mov_b32_e32 v63, v207
	v_mov_b32_e32 v64, v200
	v_mov_b32_e32 v65, v201
	v_mov_b32_e32 v66, v202
	v_mov_b32_e32 v67, v203
	v_cmp_lt_i32_e32 vcc, -1, v72
	s_and_saveexec_b64 s[42:43], vcc
	s_cbranch_execz .LBB0_736
	v_mov_b32_e32 v73, v133
	v_lshlrev_b64 v[68:69], 13, v[72:73]
	v_lshl_add_u64 v[68:69], v[76:77], 0, v[68:69]
	global_load_dwordx4 v[232:235], v[68:69], off
	v_add_co_u32_e32 v108, vcc, s36, v68
	s_mov_b32 s2, 0x400000
	s_nop 0
	v_addc_co_u32_e32 v109, vcc, 0, v69, vcc
	v_add_co_u32_e32 v138, vcc, s2, v68
	s_mov_b32 s2, 0x401000
	s_nop 0
	v_addc_co_u32_e32 v139, vcc, 0, v69, vcc
	v_add_co_u32_e32 v140, vcc, s2, v68
	s_mov_b32 s2, 0x801000
	s_nop 0
	v_addc_co_u32_e32 v141, vcc, 0, v69, vcc
	s_mov_b64 s[4:5], 0x1000
	v_lshl_add_u64 v[88:89], v[82:83], 0, s[4:5]
	s_mov_b64 s[4:5], 0x1400
	v_lshl_add_u64 v[86:87], v[82:83], 0, s[4:5]
	s_mov_b64 s[4:5], 0x1800
	v_lshl_add_u64 v[84:85], v[82:83], 0, s[4:5]
	s_mov_b64 s[4:5], 0x1c00
	v_lshl_add_u64 v[80:81], v[82:83], 0, s[4:5]
	global_load_dwordx4 v[236:239], v[68:69], off offset:1024
	global_load_dwordx4 v[240:243], v[68:69], off offset:2048
	global_load_dwordx4 v[244:247], v[68:69], off offset:3072
	global_load_dwordx4 v[200:203], v[108:109], off
	global_load_dwordx4 v[204:207], v[108:109], off offset:1024
	global_load_dwordx4 v[208:211], v[108:109], off offset:2048
	global_load_dwordx4 v[212:215], v[108:109], off offset:3072
	global_load_dwordx4 v[216:219], v[140:141], off offset:-4096
	global_load_dwordx4 v[220:223], v[138:139], off offset:1024
	global_load_dwordx4 v[224:227], v[138:139], off offset:2048
	global_load_dwordx4 v[228:231], v[138:139], off offset:3072
	v_add_co_u32_e32 v138, vcc, s14, v68
	s_waitcnt vmcnt(0)
	v_pk_add_f32 v[70:71], v[234:235], 0 op_sel_hi:[1, 0]
	v_pk_add_f32 v[94:95], v[232:233], 0 op_sel_hi:[1, 0]
	v_pk_add_f32 v[96:97], v[238:239], 0 op_sel_hi:[1, 0]
	v_pk_add_f32 v[98:99], v[236:237], 0 op_sel_hi:[1, 0]
	v_pk_add_f32 v[100:101], v[242:243], 0 op_sel_hi:[1, 0]
	v_pk_add_f32 v[102:103], v[240:241], 0 op_sel_hi:[1, 0]
	v_pk_add_f32 v[104:105], v[246:247], 0 op_sel_hi:[1, 0]
	v_pk_add_f32 v[106:107], v[244:245], 0 op_sel_hi:[1, 0]
	v_pk_add_f32 v[110:111], v[202:203], 0 op_sel_hi:[1, 0]
	v_pk_add_f32 v[112:113], v[200:201], 0 op_sel_hi:[1, 0]
	v_pk_add_f32 v[114:115], v[206:207], 0 op_sel_hi:[1, 0]
	v_pk_add_f32 v[116:117], v[204:205], 0 op_sel_hi:[1, 0]
	v_pk_add_f32 v[118:119], v[210:211], 0 op_sel_hi:[1, 0]
	v_pk_add_f32 v[120:121], v[208:209], 0 op_sel_hi:[1, 0]
	v_pk_add_f32 v[108:109], v[214:215], 0 op_sel_hi:[1, 0]
	v_pk_add_f32 v[130:131], v[212:213], 0 op_sel_hi:[1, 0]
	v_pk_add_f32 v[70:71], v[70:71], v[218:219]
	v_pk_add_f32 v[94:95], v[94:95], v[216:217]
	v_pk_add_f32 v[96:97], v[96:97], v[222:223]
	v_pk_add_f32 v[98:99], v[98:99], v[220:221]
	v_pk_add_f32 v[100:101], v[100:101], v[226:227]
	v_pk_add_f32 v[102:103], v[102:103], v[224:225]
	v_pk_add_f32 v[104:105], v[104:105], v[230:231]
	v_pk_add_f32 v[106:107], v[106:107], v[228:229]
	global_load_dwordx4 v[232:235], v[140:141], off
	v_addc_co_u32_e32 v139, vcc, 0, v69, vcc
	global_load_dwordx4 v[236:239], v[140:141], off offset:1024
	global_load_dwordx4 v[240:243], v[140:141], off offset:2048
	global_load_dwordx4 v[244:247], v[140:141], off offset:3072
	v_add_co_u32_e32 v140, vcc, s2, v68
	s_mov_b32 s2, 0xc00000
	s_nop 0
	v_addc_co_u32_e32 v141, vcc, 0, v69, vcc
	global_load_dwordx4 v[200:203], v[140:141], off offset:-4096
	global_load_dwordx4 v[204:207], v[138:139], off offset:1024
	global_load_dwordx4 v[208:211], v[138:139], off offset:2048
	global_load_dwordx4 v[212:215], v[138:139], off offset:3072
	global_load_dwordx4 v[216:219], v[140:141], off
	global_load_dwordx4 v[220:223], v[140:141], off offset:1024
	global_load_dwordx4 v[224:227], v[140:141], off offset:2048
	s_waitcnt vmcnt(0)
; template <int MODE>
; __device__ __forceinline__ void norm_row(const Params& p, const f32x4 (&g)[8], int r, int lane, int nparts, float pscale) {
;     ...
;         for (int k = 0; k < nparts; ++k) {
; #pragma unroll
;             for (int i = 0; i < 8; ++i) a[i] += *(const f32x4*)(pp + (size_t)k * (512 * 2048) + i * 256);
	v_pk_add_f32 v[110:111], v[110:111], v[234:235]
	v_pk_add_f32 v[112:113], v[112:113], v[232:233]
	v_pk_add_f32 v[114:115], v[114:115], v[238:239]
	v_pk_add_f32 v[116:117], v[116:117], v[236:237]
	v_pk_add_f32 v[118:119], v[118:119], v[242:243]
	v_pk_add_f32 v[120:121], v[120:121], v[240:241]
	v_pk_add_f32 v[108:109], v[108:109], v[246:247]
	v_pk_add_f32 v[130:131], v[130:131], v[244:245]
	v_pk_add_f32 v[70:71], v[70:71], v[202:203]
	v_pk_add_f32 v[94:95], v[94:95], v[200:201]
	v_pk_add_f32 v[96:97], v[96:97], v[206:207]
	v_pk_add_f32 v[98:99], v[98:99], v[204:205]
	v_pk_add_f32 v[100:101], v[100:101], v[210:211]
	v_pk_add_f32 v[102:103], v[102:103], v[208:209]
	v_pk_add_f32 v[104:105], v[104:105], v[214:215]
	v_pk_add_f32 v[106:107], v[106:107], v[212:213]
	v_pk_add_f32 v[138:139], v[110:111], v[218:219]
	v_pk_add_f32 v[142:143], v[112:113], v[216:217]
	v_pk_add_f32 v[144:145], v[114:115], v[222:223]
	v_pk_add_f32 v[146:147], v[116:117], v[220:221]
	v_pk_add_f32 v[148:149], v[118:119], v[226:227]
	v_pk_add_f32 v[120:121], v[120:121], v[224:225]
	global_load_dwordx4 v[228:231], v[140:141], off offset:3072
	v_add_co_u32_e32 v140, vcc, s2, v68
	s_mov_b32 s2, 0xc01000
	s_nop 0
	v_addc_co_u32_e32 v141, vcc, 0, v69, vcc
	v_add_co_u32_e32 v152, vcc, s2, v68
	s_mov_b32 s2, 0x1000000
	s_nop 0
	v_addc_co_u32_e32 v153, vcc, 0, v69, vcc
	global_load_dwordx4 v[232:235], v[152:153], off offset:-4096
	global_load_dwordx4 v[236:239], v[140:141], off offset:1024
	global_load_dwordx4 v[240:243], v[140:141], off offset:2048
	global_load_dwordx4 v[244:247], v[140:141], off offset:3072
	global_load_dwordx4 v[200:203], v[152:153], off
	global_load_dwordx4 v[204:207], v[152:153], off offset:1024
	global_load_dwordx4 v[208:211], v[152:153], off offset:3072
	global_load_dwordx4 v[212:215], v[152:153], off offset:2048
	s_waitcnt vmcnt(0)
	v_pk_add_f32 v[150:151], v[108:109], v[230:231]
	v_pk_add_f32 v[130:131], v[130:131], v[228:229]
	v_pk_add_f32 v[116:117], v[70:71], v[234:235]
	v_pk_add_f32 v[118:119], v[94:95], v[232:233]
	v_pk_add_f32 v[112:113], v[96:97], v[238:239]
	v_pk_add_f32 v[114:115], v[98:99], v[236:237]
	v_pk_add_f32 v[108:109], v[100:101], v[242:243]
	v_pk_add_f32 v[110:111], v[102:103], v[240:241]
	v_pk_add_f32 v[104:105], v[104:105], v[246:247]
	v_pk_add_f32 v[106:107], v[106:107], v[244:245]
	v_pk_add_f32 v[100:101], v[138:139], v[202:203]
	v_pk_add_f32 v[102:103], v[142:143], v[200:201]
	v_pk_add_f32 v[96:97], v[144:145], v[206:207]
	v_pk_add_f32 v[98:99], v[146:147], v[204:205]
	v_pk_add_f32 v[70:71], v[150:151], v[210:211]
	v_pk_add_f32 v[94:95], v[120:121], v[212:213]
	v_add_co_u32_e32 v120, vcc, s2, v68
	s_mov_b32 s2, 0x1001000
	s_nop 0
	v_addc_co_u32_e32 v121, vcc, 0, v69, vcc
	s_waitcnt vmcnt(0)
	v_pk_add_f32 v[90:91], v[130:131], v[208:209]
	v_add_co_u32_e32 v130, vcc, s2, v68
	s_nop 0
	v_addc_co_u32_e32 v131, vcc, 0, v69, vcc
	global_load_dwordx4 v[216:219], v[130:131], off offset:-4096
	s_mov_b32 s2, 0x1400000
	global_load_dwordx4 v[220:223], v[120:121], off offset:1024
	global_load_dwordx4 v[224:227], v[120:121], off offset:2048
	global_load_dwordx4 v[228:231], v[120:121], off offset:3072
	global_load_dwordx4 v[232:235], v[130:131], off
	global_load_dwordx4 v[236:239], v[130:131], off offset:1024
	global_load_dwordx4 v[240:243], v[130:131], off offset:2048
	global_load_dwordx4 v[244:247], v[130:131], off offset:3072
	s_waitcnt vmcnt(0)
	v_pk_add_f32 v[92:93], v[148:149], v[214:215]
	v_pk_add_f32 v[140:141], v[116:117], v[218:219]
	v_pk_add_f32 v[138:139], v[118:119], v[216:217]
	v_pk_add_f32 v[118:119], v[112:113], v[222:223]
	v_pk_add_f32 v[116:117], v[114:115], v[220:221]
	v_pk_add_f32 v[114:115], v[108:109], v[226:227]
	v_pk_add_f32 v[112:113], v[110:111], v[224:225]
	v_pk_add_f32 v[120:121], v[104:105], v[230:231]
	v_pk_add_f32 v[142:143], v[106:107], v[228:229]
	v_pk_add_f32 v[144:145], v[100:101], v[234:235]
	v_pk_add_f32 v[146:147], v[102:103], v[232:233]
	v_pk_add_f32 v[102:103], v[96:97], v[238:239]
	v_pk_add_f32 v[100:101], v[98:99], v[236:237]
	v_pk_add_f32 v[148:149], v[92:93], v[242:243]
	v_pk_add_f32 v[150:151], v[94:95], v[240:241]
	v_pk_add_f32 v[130:131], v[70:71], v[246:247]
	v_add_co_u32_e32 v94, vcc, s2, v68
	s_mov_b32 s2, 0x1401000
	s_nop 0
	v_addc_co_u32_e32 v95, vcc, 0, v69, vcc
	v_add_co_u32_e32 v154, vcc, s2, v68
	s_nop 0
	v_addc_co_u32_e32 v155, vcc, 0, v69, vcc
	global_load_dwordx4 v[200:203], v[154:155], off offset:-4096
	s_mov_b32 s2, 0x1800000
	global_load_dwordx4 v[204:207], v[94:95], off offset:1024
	global_load_dwordx4 v[208:211], v[154:155], off offset:3072
	global_load_dwordx4 v[212:215], v[94:95], off offset:2048
	global_load_dwordx4 v[216:219], v[94:95], off offset:3072
	global_load_dwordx4 v[220:223], v[154:155], off
	s_waitcnt vmcnt(0)
	v_pk_add_f32 v[152:153], v[90:91], v[244:245]
	v_pk_add_f32 v[108:109], v[140:141], v[202:203]
	v_pk_add_f32 v[110:111], v[138:139], v[200:201]
	v_pk_add_f32 v[96:97], v[118:119], v[206:207]
	v_pk_add_f32 v[98:99], v[116:117], v[204:205]
	v_pk_add_f32 v[70:71], v[114:115], v[214:215]
	v_pk_add_f32 v[90:91], v[112:113], v[212:213]
	v_pk_add_f32 v[104:105], v[120:121], v[218:219]
	v_pk_add_f32 v[106:107], v[142:143], v[216:217]
	v_add_co_u32_e32 v120, vcc, s2, v68
	s_mov_b32 s2, 0x1801000
	s_nop 0
	v_addc_co_u32_e32 v121, vcc, 0, v69, vcc
	global_load_dwordx4 v[224:227], v[154:155], off offset:1024
	global_load_dwordx4 v[236:239], v[154:155], off offset:2048
	s_waitcnt vmcnt(0)
; template <int MODE>
; __device__ __forceinline__ void norm_row(const Params& p, const f32x4 (&g)[8], int r, int lane, int nparts, float pscale) {
;     ...
;         for (int k = 0; k < nparts; ++k) {
; #pragma unroll
;             for (int i = 0; i < 8; ++i) a[i] += *(const f32x4*)(pp + (size_t)k * (512 * 2048) + i * 256);
	v_pk_add_f32 v[116:117], v[144:145], v[222:223]
	v_pk_add_f32 v[118:119], v[146:147], v[220:221]
	v_pk_add_f32 v[112:113], v[102:103], v[226:227]
	v_pk_add_f32 v[114:115], v[100:101], v[224:225]
	v_pk_add_f32 v[102:103], v[150:151], v[236:237]
	v_pk_add_f32 v[92:93], v[130:131], v[210:211]
	v_add_co_u32_e32 v130, vcc, s2, v68
	s_nop 0
	v_addc_co_u32_e32 v131, vcc, 0, v69, vcc
	global_load_dwordx4 v[228:231], v[130:131], off offset:-4096
	s_mov_b32 s2, 0x1c00000
	global_load_dwordx4 v[232:235], v[120:121], off offset:1024
	global_load_dwordx4 v[240:243], v[120:121], off offset:2048
	global_load_dwordx4 v[244:247], v[120:121], off offset:3072
	global_load_dwordx4 v[200:203], v[130:131], off
	global_load_dwordx4 v[204:207], v[130:131], off offset:1024
	global_load_dwordx4 v[212:215], v[130:131], off offset:2048
	global_load_dwordx4 v[216:219], v[130:131], off offset:3072
	s_waitcnt vmcnt(0)
	v_pk_add_f32 v[100:101], v[148:149], v[238:239]
	v_pk_add_f32 v[94:95], v[152:153], v[208:209]
	v_pk_add_f32 v[140:141], v[108:109], v[230:231]
	v_pk_add_f32 v[138:139], v[110:111], v[228:229]
	v_pk_add_f32 v[110:111], v[96:97], v[234:235]
	v_pk_add_f32 v[108:109], v[98:99], v[232:233]
	v_pk_add_f32 v[70:71], v[70:71], v[242:243]
	v_pk_add_f32 v[142:143], v[90:91], v[240:241]
	v_pk_add_f32 v[104:105], v[104:105], v[246:247]
	v_pk_add_f32 v[106:107], v[106:107], v[244:245]
	v_pk_add_f32 v[116:117], v[116:117], v[202:203]
	v_pk_add_f32 v[118:119], v[118:119], v[200:201]
	v_pk_add_f32 v[112:113], v[112:113], v[206:207]
	v_pk_add_f32 v[114:115], v[114:115], v[204:205]
	v_pk_add_f32 v[100:101], v[100:101], v[214:215]
	v_pk_add_f32 v[102:103], v[102:103], v[212:213]
	v_pk_add_f32 v[94:95], v[94:95], v[216:217]
	v_add_co_u32_e32 v96, vcc, s2, v68
	s_mov_b32 s2, 0x1c01000
	s_nop 0
	v_addc_co_u32_e32 v97, vcc, 0, v69, vcc
	v_add_co_u32_e32 v120, vcc, s2, v68
	s_nop 0
	v_addc_co_u32_e32 v121, vcc, 0, v69, vcc
	global_load_dwordx4 v[220:223], v[120:121], off offset:-4096
	s_brev_b32 s2, 64
	global_load_dwordx4 v[224:227], v[96:97], off offset:1024
	global_load_dwordx4 v[208:211], v[96:97], off offset:2048
	global_load_dwordx4 v[236:239], v[96:97], off offset:3072
	global_load_dwordx4 v[228:231], v[120:121], off
	global_load_dwordx4 v[232:235], v[120:121], off offset:1024
	s_waitcnt vmcnt(0)
	v_pk_add_f32 v[98:99], v[92:93], v[218:219]
	v_pk_add_f32 v[130:131], v[140:141], v[222:223]
	v_pk_add_f32 v[138:139], v[138:139], v[220:221]
	v_pk_add_f32 v[110:111], v[110:111], v[226:227]
	v_pk_add_f32 v[108:109], v[108:109], v[224:225]
	v_pk_add_f32 v[70:71], v[70:71], v[210:211]
	v_pk_add_f32 v[140:141], v[142:143], v[208:209]
	v_pk_add_f32 v[96:97], v[104:105], v[238:239]
	v_pk_add_f32 v[104:105], v[106:107], v[236:237]
	v_pk_add_f32 v[106:107], v[116:117], v[230:231]
	v_pk_add_f32 v[116:117], v[118:119], v[228:229]
	v_add_co_u32_e32 v118, vcc, s2, v68
	s_mov_b32 s2, 0x2001000
	s_nop 0
	v_addc_co_u32_e32 v119, vcc, 0, v69, vcc
	global_load_dwordx4 v[240:243], v[120:121], off offset:2048
	global_load_dwordx4 v[244:247], v[120:121], off offset:3072
	v_add_co_u32_e32 v120, vcc, s2, v68
	s_mov_b32 s2, 0x2400000
	s_nop 0
	v_addc_co_u32_e32 v121, vcc, 0, v69, vcc
	global_load_dwordx4 v[200:203], v[120:121], off offset:-4096
	global_load_dwordx4 v[204:207], v[118:119], off offset:1024
	global_load_dwordx4 v[212:215], v[118:119], off offset:2048
	global_load_dwordx4 v[216:219], v[118:119], off offset:3072
	global_load_dwordx4 v[220:223], v[120:121], off
	global_load_dwordx4 v[224:227], v[120:121], off offset:1024
	global_load_dwordx4 v[208:211], v[120:121], off offset:2048
	global_load_dwordx4 v[236:239], v[120:121], off offset:3072
	s_waitcnt vmcnt(0)
	v_pk_add_f32 v[112:113], v[112:113], v[234:235]
	v_pk_add_f32 v[114:115], v[114:115], v[232:233]
	v_pk_add_f32 v[100:101], v[100:101], v[242:243]
	v_pk_add_f32 v[102:103], v[102:103], v[240:241]
	v_pk_add_f32 v[98:99], v[98:99], v[246:247]
	v_pk_add_f32 v[94:95], v[94:95], v[244:245]
	v_pk_add_f32 v[130:131], v[130:131], v[202:203]
	v_pk_add_f32 v[138:139], v[138:139], v[200:201]
	v_pk_add_f32 v[110:111], v[110:111], v[206:207]
	v_pk_add_f32 v[108:109], v[108:109], v[204:205]
	v_pk_add_f32 v[70:71], v[70:71], v[214:215]
	v_pk_add_f32 v[140:141], v[140:141], v[212:213]
	v_pk_add_f32 v[96:97], v[96:97], v[218:219]
	v_pk_add_f32 v[104:105], v[104:105], v[216:217]
	v_pk_add_f32 v[106:107], v[106:107], v[222:223]
	v_pk_add_f32 v[116:117], v[116:117], v[220:221]
	v_pk_add_f32 v[112:113], v[112:113], v[226:227]
	v_pk_add_f32 v[114:115], v[114:115], v[224:225]
	v_pk_add_f32 v[100:101], v[100:101], v[210:211]
	v_pk_add_f32 v[102:103], v[102:103], v[208:209]
	v_pk_add_f32 v[118:119], v[94:95], v[236:237]
	v_add_co_u32_e32 v94, vcc, s2, v68
	s_mov_b32 s2, 0x2401000
	s_nop 0
	v_addc_co_u32_e32 v95, vcc, 0, v69, vcc
	v_add_co_u32_e32 v120, vcc, s2, v68
	s_nop 0
	v_addc_co_u32_e32 v121, vcc, 0, v69, vcc
	global_load_dwordx4 v[228:231], v[120:121], off offset:-4096
	s_mov_b32 s2, 0x2800000
	global_load_dwordx4 v[232:235], v[94:95], off offset:1024
	global_load_dwordx4 v[240:243], v[94:95], off offset:2048
	global_load_dwordx4 v[244:247], v[94:95], off offset:3072
	global_load_dwordx4 v[200:203], v[120:121], off
	global_load_dwordx4 v[204:207], v[120:121], off offset:1024
	s_waitcnt vmcnt(0)
; template <int MODE>
; __device__ __forceinline__ void norm_row(const Params& p, const f32x4 (&g)[8], int r, int lane, int nparts, float pscale) {
;     ...
;         for (int k = 0; k < nparts; ++k) {
; #pragma unroll
;             for (int i = 0; i < 8; ++i) a[i] += *(const f32x4*)(pp + (size_t)k * (512 * 2048) + i * 256);
;         }
; #pragma unroll
;         for (int i = 0; i < 8; ++i) { v[i] += pscale * a[i]; *(f32x4*)(X + (size_t)r * 2048 + i * 256 + lane * 4) = v[i]; }
	v_pk_add_f32 v[98:99], v[98:99], v[238:239]
	v_pk_add_f32 v[130:131], v[130:131], v[230:231]
	v_pk_add_f32 v[138:139], v[138:139], v[228:229]
	v_pk_add_f32 v[110:111], v[110:111], v[234:235]
	v_pk_add_f32 v[108:109], v[108:109], v[232:233]
	v_pk_add_f32 v[142:143], v[70:71], v[242:243]
	v_pk_add_f32 v[140:141], v[140:141], v[240:241]
	v_pk_add_f32 v[144:145], v[96:97], v[246:247]
	v_pk_add_f32 v[146:147], v[104:105], v[244:245]
	v_pk_add_f32 v[148:149], v[106:107], v[202:203]
	v_pk_add_f32 v[116:117], v[116:117], v[200:201]
	v_add_co_u32_e32 v106, vcc, s2, v68
	s_mov_b32 s2, 0x2801000
	s_nop 0
	v_addc_co_u32_e32 v107, vcc, 0, v69, vcc
	v_add_co_u32_e32 v158, vcc, s2, v68
	s_nop 1
	v_addc_co_u32_e32 v159, vcc, 0, v69, vcc
	global_load_dwordx4 v[212:215], v[158:159], off offset:-4096
	s_waitcnt vmcnt(0)
	v_mov_b32_e32 v68, v212
	v_mov_b32_e32 v69, v213
	v_mov_b32_e32 v70, v214
	v_mov_b32_e32 v71, v215
	v_mov_b32_e32 v90, v204
	v_mov_b32_e32 v91, v205
	v_mov_b32_e32 v92, v206
	v_mov_b32_e32 v93, v207
	s_waitcnt vmcnt(1)
	v_pk_add_f32 v[150:151], v[112:113], v[92:93]
	v_pk_add_f32 v[152:153], v[114:115], v[90:91]
	global_load_dwordx4 v[90:93], v[120:121], off offset:2048
	s_waitcnt vmcnt(1)
	v_pk_add_f32 v[96:97], v[138:139], v[68:69]
	s_nop 0
	v_pk_fma_f32 v[64:65], v[96:97], 0.5, v[64:65] op_sel_hi:[1,0,1]
	s_waitcnt vmcnt(0)
	v_pk_add_f32 v[154:155], v[100:101], v[92:93]
	global_load_dwordx4 v[92:95], v[120:121], off offset:3072
	v_pk_add_f32 v[156:157], v[102:103], v[90:91]
	s_waitcnt vmcnt(0)
	v_pk_add_f32 v[90:91], v[98:99], v[94:95]
	v_pk_add_f32 v[94:95], v[130:131], v[70:71]
	global_load_dwordx4 v[68:71], v[106:107], off offset:1024
	v_pk_add_f32 v[92:93], v[118:119], v[92:93]
	v_pk_fma_f32 v[66:67], v[94:95], 0.5, v[66:67] op_sel_hi:[1,0,1]
	global_store_dwordx4 v[82:83], v[64:67], off
	s_waitcnt vmcnt(1)
	v_pk_add_f32 v[98:99], v[110:111], v[70:71]
	v_pk_add_f32 v[100:101], v[108:109], v[68:69]
	global_load_dwordx4 v[68:71], v[106:107], off offset:2048
	v_pk_fma_f32 v[62:63], v[98:99], 0.5, v[62:63] op_sel_hi:[1,0,1]
	v_pk_fma_f32 v[60:61], v[100:101], 0.5, v[60:61] op_sel_hi:[1,0,1]
	global_store_dwordx4 v[82:83], v[60:63], off offset:1024
	s_waitcnt vmcnt(1)
	v_pk_add_f32 v[102:103], v[142:143], v[70:71]
	v_pk_add_f32 v[104:105], v[140:141], v[68:69]
	global_load_dwordx4 v[68:71], v[106:107], off offset:3072
	v_pk_fma_f32 v[58:59], v[102:103], 0.5, v[58:59] op_sel_hi:[1,0,1]
	v_pk_fma_f32 v[56:57], v[104:105], 0.5, v[56:57] op_sel_hi:[1,0,1]
	global_store_dwordx4 v[82:83], v[56:59], off offset:2048
	s_waitcnt vmcnt(1)
	v_pk_add_f32 v[106:107], v[144:145], v[70:71]
	v_pk_add_f32 v[108:109], v[146:147], v[68:69]
	global_load_dwordx4 v[68:71], v[158:159], off
	v_pk_fma_f32 v[54:55], v[106:107], 0.5, v[54:55] op_sel_hi:[1,0,1]
	v_pk_fma_f32 v[52:53], v[108:109], 0.5, v[52:53] op_sel_hi:[1,0,1]
	global_store_dwordx4 v[82:83], v[52:55], off offset:3072
	s_waitcnt vmcnt(1)
	v_pk_add_f32 v[110:111], v[148:149], v[70:71]
	v_pk_add_f32 v[112:113], v[116:117], v[68:69]
	global_load_dwordx4 v[68:71], v[158:159], off offset:1024
	v_pk_fma_f32 v[50:51], v[110:111], 0.5, v[50:51] op_sel_hi:[1,0,1]
	v_pk_fma_f32 v[48:49], v[112:113], 0.5, v[48:49] op_sel_hi:[1,0,1]
	global_store_dwordx4 v[88:89], v[48:51], off
	s_waitcnt vmcnt(1)
	v_pk_add_f32 v[114:115], v[150:151], v[70:71]
	v_pk_add_f32 v[116:117], v[152:153], v[68:69]
	global_load_dwordx4 v[68:71], v[158:159], off offset:2048
	v_pk_fma_f32 v[46:47], v[114:115], 0.5, v[46:47] op_sel_hi:[1,0,1]
	v_pk_fma_f32 v[44:45], v[116:117], 0.5, v[44:45] op_sel_hi:[1,0,1]
	global_store_dwordx4 v[86:87], v[44:47], off
	s_waitcnt vmcnt(1)
	v_pk_add_f32 v[118:119], v[154:155], v[70:71]
	v_pk_add_f32 v[120:121], v[156:157], v[68:69]
	global_load_dwordx4 v[68:71], v[158:159], off offset:3072
	v_pk_fma_f32 v[42:43], v[118:119], 0.5, v[42:43] op_sel_hi:[1,0,1]
	v_pk_fma_f32 v[40:41], v[120:121], 0.5, v[40:41] op_sel_hi:[1,0,1]
	global_store_dwordx4 v[84:85], v[40:43], off
	s_waitcnt vmcnt(1)
	v_pk_add_f32 v[70:71], v[90:91], v[70:71]
	v_pk_add_f32 v[68:69], v[92:93], v[68:69]
	v_pk_fma_f32 v[38:39], v[70:71], 0.5, v[38:39] op_sel_hi:[1,0,1]
	v_pk_fma_f32 v[36:37], v[68:69], 0.5, v[36:37] op_sel_hi:[1,0,1]
	global_store_dwordx4 v[80:81], v[36:39], off
	s_branch .LBB0_736

; #define PG8_STAGE(bufoff, gbase, voff) do { _Pragma("unroll") for (int _i = 0; _i < 2; ++_i) \
;         __builtin_amdgcn_global_load_lds((const unsigned*)((const char*)(gbase) + (voff)[_i]), (LAS unsigned*)(lds + (bufoff) + ldsw + _i * 8192), 16, 0, 0); } while (0)
; #define PG8_LDA(dst, b, h) do { _Pragma("unroll") for (int m = 0; m < 4; ++m) _Pragma("unroll") for (int k = 0; k < 2; ++k) dst[m][k] = *(const LAS bf16x8*)(lds + PG8_SA(b, h) + aoff + m * 2048 + k * 1024); } while (0)
; #define PG8_LDB(dst, b, h) do { _Pragma("unroll") for (int n = 0; n < 2; ++n) _Pragma("unroll") for (int k = 0; k < 2; ++k) dst[n][k] = *(const LAS bf16x8*)(lds + PG8_SB(b, h) + boff + n * 2048 + k * 1024); } while (0)
; #define PG8_MMA(ai, bj, At, Bt) do { __builtin_amdgcn_s_setprio(1); _Pragma("unroll") for (int m = 0; m < 4; ++m) _Pragma("unroll") for (int n = 0; n < 2; ++n) _Pragma("unroll") for (int k = 0; k < 2; ++k) \
;         acc[ai][bj][m][n] = __builtin_amdgcn_mfma_f32_16x16x32_bf16(Bt[n][k], At[m][k], acc[ai][bj][m][n], 0, 0, 0); __builtin_amdgcn_s_setprio(0); } while (0)
; #define PG8_WAIT_V(n) asm volatile("s_waitcnt vmcnt(" #n ")" ::: "memory")
; #define PG8_WAIT_L(n) asm volatile("s_waitcnt lgkmcnt(" #n ")" ::: "memory")
; template <class Epi, class Sched, int LD>
; __device__ __forceinline__ void gemm_phase(LAS unsigned char* lds, const Gemm g, const Sched& S, const Epi& E) {
;     ...
;         for (int t = 0; t < nt; t += 2) {
;             const bool last = (t == nt - 2);
;             const char* a1 = cA + (size_t)(t + 1) * kstep;
;             const char* a2 = last ? nA : cA + (size_t)(t + 2) * kstep; const char* b2 = last ? nB : cB + (size_t)(t + 2) * kstep;
;             const char* a3 = a2 + kstep; const char* b3 = b2 + kstep;
;             PG8_LDB(B0, 0, 0); PG8_SCHED; PG8_LDA(At, 0, 0); PG8_STAGE(PG8_SA(1, 1), a1 + hstep, voffA);
;             PG8_WAIT_L(8); PG8_BAR; PG8_WAIT_L(0); PG8_MMA(0, 0, At, B0); PG8_BAR; PG8_SCHED;
;             PG8_LDB(B1, 0, 1); PG8_STAGE(PG8_SB(0, 0), b2, voffB);
;             PG8_BAR; PG8_WAIT_L(0); PG8_MMA(0, 1, At, B1); PG8_BAR;
;             PG8_LDA(At, 0, 1); PG8_STAGE(PG8_SA(0, 0), a2, voffA);
;             PG8_BAR; PG8_WAIT_L(0); PG8_MMA(1, 0, At, B0); PG8_BAR; PG8_SCHED;
;             PG8_STAGE(PG8_SB(0, 1), b2 + hstep, voffB);
;             PG8_WAIT_V(6); PG8_BAR; PG8_MMA(1, 1, At, B1); PG8_BAR;
.LBB0_899:
	s_add_u32 s4, s50, 0x4000
	s_addc_u32 s5, s51, 0
	s_cmp_eq_u32 s70, 28
	s_cselect_b32 s4, s48, s4
	s_cselect_b32 s5, s49, s5
	s_cselect_b32 s54, s40, s45
	s_cselect_b32 s55, s41, s47
	s_add_u32 s56, s4, 0x8000
	s_addc_u32 s57, s5, 0
	s_add_i32 s71, 0, 0x10000
	ds_read_b128 v[146:149], v228
	ds_read_b128 v[150:153], v228 offset:1024
	ds_read_b128 v[154:157], v228 offset:2048
	ds_read_b128 v[176:179], v228 offset:3072
	s_add_i32 m0, s29, 0xc000
	ds_read_b128 v[180:183], v144
	ds_read_b128 v[184:187], v144 offset:1024
	ds_read_b128 v[188:191], v144 offset:2048
	ds_read_b128 v[192:195], v144 offset:3072
	ds_read_b128 v[196:199], v144 offset:4096
	ds_read_b128 v[200:203], v144 offset:5120
	ds_read_b128 v[204:207], v144 offset:6144
	ds_read_b128 v[208:211], v144 offset:7168
	global_load_lds_dwordx4 v138, s[50:51]
	s_add_i32 m0, s29, 0xe000
	s_nop 0
	global_load_lds_dwordx4 v140, s[50:51]
	s_waitcnt lgkmcnt(8)
	s_barrier
	s_waitcnt lgkmcnt(0)
	s_setprio 0
	v_mfma_f32_16x16x32_bf16 v[128:131], v[146:149], v[180:183], v[128:131]
	v_mfma_f32_16x16x32_bf16 v[120:123], v[154:157], v[180:183], v[120:123]
	v_mfma_f32_16x16x32_bf16 v[112:115], v[146:149], v[188:191], v[112:115]
	v_mfma_f32_16x16x32_bf16 v[104:107], v[154:157], v[188:191], v[104:107]
	v_mfma_f32_16x16x32_bf16 v[96:99], v[146:149], v[196:199], v[96:99]
	v_mfma_f32_16x16x32_bf16 v[88:91], v[154:157], v[196:199], v[88:91]
	v_mfma_f32_16x16x32_bf16 v[80:83], v[146:149], v[204:207], v[80:83]
	v_mfma_f32_16x16x32_bf16 v[72:75], v[154:157], v[204:207], v[72:75]
	v_mfma_f32_16x16x32_bf16 v[128:131], v[150:153], v[184:187], v[128:131]
	v_mfma_f32_16x16x32_bf16 v[120:123], v[176:179], v[184:187], v[120:123]
	v_mfma_f32_16x16x32_bf16 v[112:115], v[150:153], v[192:195], v[112:115]
	v_mfma_f32_16x16x32_bf16 v[104:107], v[176:179], v[192:195], v[104:107]
	v_mfma_f32_16x16x32_bf16 v[96:99], v[150:153], v[200:203], v[96:99]
	v_mfma_f32_16x16x32_bf16 v[88:91], v[176:179], v[200:203], v[88:91]
	s_setprio 3
	s_barrier
	v_mfma_f32_16x16x32_bf16 v[80:83], v[150:153], v[208:211], v[80:83]
	v_mfma_f32_16x16x32_bf16 v[72:75], v[176:179], v[208:211], v[72:75]
	s_setprio 2
	s_add_i32 s74, 0, 0x14000
	s_add_i32 s71, s71, s28
	s_mov_b32 m0, s71
	ds_read_b128 v[212:215], v228 offset:16384
	ds_read_b128 v[216:219], v228 offset:17408
	ds_read_b128 v[220:223], v228 offset:18432
	ds_read_b128 v[224:227], v228 offset:19456
	global_load_lds_dwordx4 v138, s[54:55]
	s_add_i32 m0, s71, 0x2000
	s_nop 0
	global_load_lds_dwordx4 v140, s[54:55]
	s_barrier
	s_waitcnt lgkmcnt(0)
	s_setprio 0
	v_mfma_f32_16x16x32_bf16 v[124:127], v[212:215], v[180:183], v[124:127]
	v_mfma_f32_16x16x32_bf16 v[116:119], v[220:223], v[180:183], v[116:119]
	v_mfma_f32_16x16x32_bf16 v[108:111], v[212:215], v[188:191], v[108:111]
	v_mfma_f32_16x16x32_bf16 v[100:103], v[220:223], v[188:191], v[100:103]
	v_mfma_f32_16x16x32_bf16 v[92:95], v[212:215], v[196:199], v[92:95]
	v_mfma_f32_16x16x32_bf16 v[84:87], v[220:223], v[196:199], v[84:87]
	v_mfma_f32_16x16x32_bf16 v[76:79], v[212:215], v[204:207], v[76:79]
	v_mfma_f32_16x16x32_bf16 v[68:71], v[220:223], v[204:207], v[68:71]
	v_mfma_f32_16x16x32_bf16 v[124:127], v[216:219], v[184:187], v[124:127]
	v_mfma_f32_16x16x32_bf16 v[116:119], v[224:227], v[184:187], v[116:119]
	v_mfma_f32_16x16x32_bf16 v[108:111], v[216:219], v[192:195], v[108:111]
	v_mfma_f32_16x16x32_bf16 v[100:103], v[224:227], v[192:195], v[100:103]
	v_mfma_f32_16x16x32_bf16 v[92:95], v[216:219], v[200:203], v[92:95]
	v_mfma_f32_16x16x32_bf16 v[84:87], v[224:227], v[200:203], v[84:87]
	v_mfma_f32_16x16x32_bf16 v[76:79], v[216:219], v[208:211], v[76:79]
	v_mfma_f32_16x16x32_bf16 v[68:71], v[224:227], v[208:211], v[68:71]
	s_setprio 2
	s_mov_b32 m0, s29
	s_barrier
	ds_read_b128 v[180:183], v144 offset:16384
	ds_read_b128 v[184:187], v144 offset:17408
	ds_read_b128 v[188:191], v144 offset:18432
	ds_read_b128 v[192:195], v144 offset:19456
	ds_read_b128 v[196:199], v144 offset:20480
	ds_read_b128 v[200:203], v144 offset:21504
	ds_read_b128 v[204:207], v144 offset:22528
	ds_read_b128 v[208:211], v144 offset:23552
	global_load_lds_dwordx4 v138, s[4:5]
	s_mov_b32 m0, s39
	s_nop 0
	global_load_lds_dwordx4 v140, s[4:5]
	s_barrier
	s_waitcnt lgkmcnt(0)
	s_setprio 0
	v_mfma_f32_16x16x32_bf16 v[64:67], v[146:149], v[180:183], v[64:67]
	v_mfma_f32_16x16x32_bf16 v[56:59], v[154:157], v[180:183], v[56:59]
	v_mfma_f32_16x16x32_bf16 v[48:51], v[146:149], v[188:191], v[48:51]
	v_mfma_f32_16x16x32_bf16 v[40:43], v[154:157], v[188:191], v[40:43]
	v_mfma_f32_16x16x32_bf16 v[32:35], v[146:149], v[196:199], v[32:35]
	v_mfma_f32_16x16x32_bf16 v[24:27], v[154:157], v[196:199], v[24:27]
	v_mfma_f32_16x16x32_bf16 v[16:19], v[146:149], v[204:207], v[16:19]
	v_mfma_f32_16x16x32_bf16 v[8:11], v[154:157], v[204:207], v[8:11]
	v_mfma_f32_16x16x32_bf16 v[64:67], v[150:153], v[184:187], v[64:67]
	v_mfma_f32_16x16x32_bf16 v[56:59], v[176:179], v[184:187], v[56:59]
	v_mfma_f32_16x16x32_bf16 v[48:51], v[150:153], v[192:195], v[48:51]
	v_mfma_f32_16x16x32_bf16 v[40:43], v[176:179], v[192:195], v[40:43]
	v_mfma_f32_16x16x32_bf16 v[32:35], v[150:153], v[200:203], v[32:35]
	v_mfma_f32_16x16x32_bf16 v[24:27], v[176:179], v[200:203], v[24:27]
	s_setprio 3
	s_barrier
	v_mfma_f32_16x16x32_bf16 v[16:19], v[150:153], v[208:211], v[16:19]
	v_mfma_f32_16x16x32_bf16 v[8:11], v[176:179], v[208:211], v[8:11]
	s_setprio 2
	s_add_u32 s72, s54, 0x4000
	s_addc_u32 s73, s55, 0
	s_add_i32 s71, s74, s28
	s_mov_b32 m0, s71
	s_nop 0
	global_load_lds_dwordx4 v138, s[72:73]
	s_add_i32 m0, s71, 0x2000
	s_nop 0
	global_load_lds_dwordx4 v140, s[72:73]
	s_waitcnt vmcnt(6)
	s_barrier
; #define PG8_STAGE(bufoff, gbase, voff) do { _Pragma("unroll") for (int _i = 0; _i < 2; ++_i) \
;         __builtin_amdgcn_global_load_lds((const unsigned*)((const char*)(gbase) + (voff)[_i]), (LAS unsigned*)(lds + (bufoff) + ldsw + _i * 8192), 16, 0, 0); } while (0)
; #define PG8_LDA(dst, b, h) do { _Pragma("unroll") for (int m = 0; m < 4; ++m) _Pragma("unroll") for (int k = 0; k < 2; ++k) dst[m][k] = *(const LAS bf16x8*)(lds + PG8_SA(b, h) + aoff + m * 2048 + k * 1024); } while (0)
; #define PG8_LDB(dst, b, h) do { _Pragma("unroll") for (int n = 0; n < 2; ++n) _Pragma("unroll") for (int k = 0; k < 2; ++k) dst[n][k] = *(const LAS bf16x8*)(lds + PG8_SB(b, h) + boff + n * 2048 + k * 1024); } while (0)
; #define PG8_MMA(ai, bj, At, Bt) do { __builtin_amdgcn_s_setprio(1); _Pragma("unroll") for (int m = 0; m < 4; ++m) _Pragma("unroll") for (int n = 0; n < 2; ++n) _Pragma("unroll") for (int k = 0; k < 2; ++k) \
;         acc[ai][bj][m][n] = __builtin_amdgcn_mfma_f32_16x16x32_bf16(Bt[n][k], At[m][k], acc[ai][bj][m][n], 0, 0, 0); __builtin_amdgcn_s_setprio(0); } while (0)
; #define PG8_WAIT_V(n) asm volatile("s_waitcnt vmcnt(" #n ")" ::: "memory")
; #define PG8_WAIT_L(n) asm volatile("s_waitcnt lgkmcnt(" #n ")" ::: "memory")
; #define PG8_BAR __builtin_amdgcn_s_barrier()
; #define PG8_SCHED __builtin_amdgcn_sched_barrier(0)
; template <class Epi, class Sched, int LD>
; __device__ __forceinline__ void gemm_phase(LAS unsigned char* lds, const Gemm g, const Sched& S, const Epi& E) {
;     ...
;             PG8_WAIT_V(6); PG8_BAR; PG8_MMA(1, 1, At, B1); PG8_BAR;
;             PG8_LDB(B0, 1, 0); PG8_SCHED; PG8_LDA(At, 1, 0); PG8_STAGE(PG8_SA(0, 1), a2 + hstep, voffA);
;             PG8_WAIT_L(8); PG8_BAR; PG8_WAIT_L(0); PG8_MMA(0, 0, At, B0); PG8_BAR; PG8_SCHED;
;             PG8_LDB(B1, 1, 1); PG8_STAGE(PG8_SB(1, 0), b3, voffB);
;             PG8_BAR; PG8_WAIT_L(0); PG8_MMA(0, 1, At, B1); PG8_BAR;
	s_setprio 0
	v_mfma_f32_16x16x32_bf16 v[60:63], v[212:215], v[180:183], v[60:63]
	v_mfma_f32_16x16x32_bf16 v[52:55], v[220:223], v[180:183], v[52:55]
	v_mfma_f32_16x16x32_bf16 v[44:47], v[212:215], v[188:191], v[44:47]
	v_mfma_f32_16x16x32_bf16 v[36:39], v[220:223], v[188:191], v[36:39]
	v_mfma_f32_16x16x32_bf16 v[28:31], v[212:215], v[196:199], v[28:31]
	v_mfma_f32_16x16x32_bf16 v[20:23], v[220:223], v[196:199], v[20:23]
	v_mfma_f32_16x16x32_bf16 v[12:15], v[212:215], v[204:207], v[12:15]
	v_mfma_f32_16x16x32_bf16 v[4:7], v[220:223], v[204:207], v[4:7]
	v_mfma_f32_16x16x32_bf16 v[60:63], v[216:219], v[184:187], v[60:63]
	v_mfma_f32_16x16x32_bf16 v[52:55], v[224:227], v[184:187], v[52:55]
	v_mfma_f32_16x16x32_bf16 v[44:47], v[216:219], v[192:195], v[44:47]
	v_mfma_f32_16x16x32_bf16 v[36:39], v[224:227], v[192:195], v[36:39]
	v_mfma_f32_16x16x32_bf16 v[28:31], v[216:219], v[200:203], v[28:31]
	v_mfma_f32_16x16x32_bf16 v[20:23], v[224:227], v[200:203], v[20:23]
	v_mfma_f32_16x16x32_bf16 v[12:15], v[216:219], v[208:211], v[12:15]
	v_mfma_f32_16x16x32_bf16 v[4:7], v[224:227], v[208:211], v[4:7]
	s_setprio 2
	s_add_i32 s71, 0, 0x18000
	s_barrier
	ds_read_b128 v[146:149], v228 offset:32768
	ds_read_b128 v[150:153], v228 offset:33792
	ds_read_b128 v[154:157], v228 offset:34816
	ds_read_b128 v[176:179], v228 offset:35840
	s_add_u32 s4, s4, 0x4000
	s_addc_u32 s5, s5, 0
	s_mov_b32 m0, s52
	ds_read_b128 v[180:183], v144 offset:32768
	ds_read_b128 v[184:187], v144 offset:33792
	ds_read_b128 v[188:191], v144 offset:34816
	ds_read_b128 v[192:195], v144 offset:35840
	ds_read_b128 v[196:199], v144 offset:36864
	ds_read_b128 v[200:203], v144 offset:37888
	ds_read_b128 v[204:207], v144 offset:38912
	ds_read_b128 v[208:211], v144 offset:39936
	global_load_lds_dwordx4 v138, s[4:5]
	s_mov_b32 m0, s53
	s_nop 0
	global_load_lds_dwordx4 v140, s[4:5]
	s_waitcnt lgkmcnt(8)
	s_barrier
	s_waitcnt lgkmcnt(0)
	s_setprio 0
	v_mfma_f32_16x16x32_bf16 v[128:131], v[146:149], v[180:183], v[128:131]
	v_mfma_f32_16x16x32_bf16 v[120:123], v[154:157], v[180:183], v[120:123]
	v_mfma_f32_16x16x32_bf16 v[112:115], v[146:149], v[188:191], v[112:115]
	v_mfma_f32_16x16x32_bf16 v[104:107], v[154:157], v[188:191], v[104:107]
	v_mfma_f32_16x16x32_bf16 v[96:99], v[146:149], v[196:199], v[96:99]
	v_mfma_f32_16x16x32_bf16 v[88:91], v[154:157], v[196:199], v[88:91]
	v_mfma_f32_16x16x32_bf16 v[80:83], v[146:149], v[204:207], v[80:83]
	v_mfma_f32_16x16x32_bf16 v[72:75], v[154:157], v[204:207], v[72:75]
	v_mfma_f32_16x16x32_bf16 v[128:131], v[150:153], v[184:187], v[128:131]
	v_mfma_f32_16x16x32_bf16 v[120:123], v[176:179], v[184:187], v[120:123]
	v_mfma_f32_16x16x32_bf16 v[112:115], v[150:153], v[192:195], v[112:115]
	v_mfma_f32_16x16x32_bf16 v[104:107], v[176:179], v[192:195], v[104:107]
	v_mfma_f32_16x16x32_bf16 v[96:99], v[150:153], v[200:203], v[96:99]
	v_mfma_f32_16x16x32_bf16 v[88:91], v[176:179], v[200:203], v[88:91]
	s_setprio 3
	s_barrier
	v_mfma_f32_16x16x32_bf16 v[80:83], v[150:153], v[208:211], v[80:83]
	v_mfma_f32_16x16x32_bf16 v[72:75], v[176:179], v[208:211], v[72:75]
	s_setprio 2
	s_add_i32 s72, 0, 0x1c000
	s_add_u32 s4, s54, 0x8000
	s_addc_u32 s5, s55, 0
	s_add_i32 s71, s71, s28
	s_mov_b32 m0, s71
	ds_read_b128 v[212:215], v228 offset:49152
	ds_read_b128 v[216:219], v228 offset:50176
	ds_read_b128 v[220:223], v228 offset:51200
	ds_read_b128 v[224:227], v228 offset:52224
	global_load_lds_dwordx4 v138, s[4:5]
	s_add_i32 m0, s71, 0x2000
	s_nop 0
	global_load_lds_dwordx4 v140, s[4:5]
	s_barrier
	s_waitcnt lgkmcnt(0)
	s_setprio 0
	v_mfma_f32_16x16x32_bf16 v[124:127], v[212:215], v[180:183], v[124:127]
	v_mfma_f32_16x16x32_bf16 v[116:119], v[220:223], v[180:183], v[116:119]
	v_mfma_f32_16x16x32_bf16 v[108:111], v[212:215], v[188:191], v[108:111]
	v_mfma_f32_16x16x32_bf16 v[100:103], v[220:223], v[188:191], v[100:103]
	v_mfma_f32_16x16x32_bf16 v[92:95], v[212:215], v[196:199], v[92:95]
	v_mfma_f32_16x16x32_bf16 v[84:87], v[220:223], v[196:199], v[84:87]
	v_mfma_f32_16x16x32_bf16 v[76:79], v[212:215], v[204:207], v[76:79]
	v_mfma_f32_16x16x32_bf16 v[68:71], v[220:223], v[204:207], v[68:71]
	v_mfma_f32_16x16x32_bf16 v[124:127], v[216:219], v[184:187], v[124:127]
	v_mfma_f32_16x16x32_bf16 v[116:119], v[224:227], v[184:187], v[116:119]
	v_mfma_f32_16x16x32_bf16 v[108:111], v[216:219], v[192:195], v[108:111]
	v_mfma_f32_16x16x32_bf16 v[100:103], v[224:227], v[192:195], v[100:103]
	v_mfma_f32_16x16x32_bf16 v[92:95], v[216:219], v[200:203], v[92:95]
	v_mfma_f32_16x16x32_bf16 v[84:87], v[224:227], v[200:203], v[84:87]
	v_mfma_f32_16x16x32_bf16 v[76:79], v[216:219], v[208:211], v[76:79]
	v_mfma_f32_16x16x32_bf16 v[68:71], v[224:227], v[208:211], v[68:71]
	s_setprio 2
	s_mov_b32 m0, s60
	s_barrier
	ds_read_b128 v[180:183], v144 offset:49152
	ds_read_b128 v[184:187], v144 offset:50176
	ds_read_b128 v[188:191], v144 offset:51200
	ds_read_b128 v[192:195], v144 offset:52224
	ds_read_b128 v[196:199], v144 offset:53248
	ds_read_b128 v[200:203], v144 offset:54272
	ds_read_b128 v[204:207], v144 offset:55296
	ds_read_b128 v[208:211], v144 offset:56320
	global_load_lds_dwordx4 v138, s[56:57]
	s_mov_b32 m0, s61
	s_nop 0
	global_load_lds_dwordx4 v140, s[56:57]
	s_barrier
; __device__ __forceinline__ unsigned cvt_pk_bf16(float lo, float hi) { f32x2 v = {lo, hi}; bf16x2v b = __builtin_convertvector(v, bf16x2v); return __builtin_bit_cast(unsigned, b); }
; __device__ __forceinline__ float silu_f(float x) { return x * __builtin_amdgcn_rcpf(1.f + __expf(-x)); }
; #define PG8_STAGE(bufoff, gbase, voff) do { _Pragma("unroll") for (int _i = 0; _i < 2; ++_i) \
;         __builtin_amdgcn_global_load_lds((const unsigned*)((const char*)(gbase) + (voff)[_i]), (LAS unsigned*)(lds + (bufoff) + ldsw + _i * 8192), 16, 0, 0); } while (0)
; #define PG8_MMA(ai, bj, At, Bt) do { __builtin_amdgcn_s_setprio(1); _Pragma("unroll") for (int m = 0; m < 4; ++m) _Pragma("unroll") for (int n = 0; n < 2; ++n) _Pragma("unroll") for (int k = 0; k < 2; ++k) \
;         acc[ai][bj][m][n] = __builtin_amdgcn_mfma_f32_16x16x32_bf16(Bt[n][k], At[m][k], acc[ai][bj][m][n], 0, 0, 0); __builtin_amdgcn_s_setprio(0); } while (0)
; #define PG8_WAIT_V(n) asm volatile("s_waitcnt vmcnt(" #n ")" ::: "memory")
; #define PG8_WAIT_L(n) asm volatile("s_waitcnt lgkmcnt(" #n ")" ::: "memory")
;     __device__ __forceinline__ void operator()(const f32x4 (&acc)[2][2][4][2], const Unit& u, int wr, int wc, int fr, int fq) const {
;         const int row0 = u.pm * BM + wr * 64 + fr, col0 = u.pn * 128 + wc * 32 + 8 * fq;
; #pragma unroll
;         for (int ai = 0; ai < 2; ++ai)
; #pragma unroll
;             for (int m = 0; m < 4; ++m) {
;                 bf16_t* rowp = O + img_off(row0 + ai * HALF + m * 16, col0, D_FF / 64);
;                 const f32x4 g0 = acc[ai][0][m][0], g1 = acc[ai][0][m][1], u0 = acc[ai][1][m][0], u1 = acc[ai][1][m][1];
;                 u32x4 w;
;                 w.x = cvt_pk_bf16(silu_f(g0[0]) * u0[0], silu_f(g0[1]) * u0[1]); w.y = cvt_pk_bf16(silu_f(g0[2]) * u0[2], silu_f(g0[3]) * u0[3]);
;                 w.z = cvt_pk_bf16(silu_f(g1[0]) * u1[0], silu_f(g1[1]) * u1[1]); w.w = cvt_pk_bf16(silu_f(g1[2]) * u1[2], silu_f(g1[3]) * u1[3]);
;                 *(u32x4*)rowp = w;
; template <class Epi, class Sched, int LD>
; __device__ __forceinline__ void gemm_phase(LAS unsigned char* lds, const Gemm g, const Sched& S, const Epi& E) {
;     ...
;             PG8_BAR; PG8_WAIT_L(0); PG8_MMA(1, 0, At, B0); PG8_BAR; PG8_SCHED;
;             PG8_STAGE(PG8_SB(1, 1), b3 + hstep, voffB);
;             PG8_WAIT_V(6); PG8_BAR; PG8_MMA(1, 1, At, B1); PG8_BAR;
	s_waitcnt lgkmcnt(0)
	s_setprio 0
	v_mfma_f32_16x16x32_bf16 v[64:67], v[146:149], v[180:183], v[64:67]
	v_mfma_f32_16x16x32_bf16 v[56:59], v[154:157], v[180:183], v[56:59]
	v_mfma_f32_16x16x32_bf16 v[48:51], v[146:149], v[188:191], v[48:51]
	v_mfma_f32_16x16x32_bf16 v[40:43], v[154:157], v[188:191], v[40:43]
	v_mfma_f32_16x16x32_bf16 v[32:35], v[146:149], v[196:199], v[32:35]
	v_mfma_f32_16x16x32_bf16 v[24:27], v[154:157], v[196:199], v[24:27]
	v_mfma_f32_16x16x32_bf16 v[16:19], v[146:149], v[204:207], v[16:19]
	v_mfma_f32_16x16x32_bf16 v[8:11], v[154:157], v[204:207], v[8:11]
	v_mfma_f32_16x16x32_bf16 v[64:67], v[150:153], v[184:187], v[64:67]
	v_mfma_f32_16x16x32_bf16 v[56:59], v[176:179], v[184:187], v[56:59]
	v_mfma_f32_16x16x32_bf16 v[48:51], v[150:153], v[192:195], v[48:51]
	v_mfma_f32_16x16x32_bf16 v[40:43], v[176:179], v[192:195], v[40:43]
	v_mfma_f32_16x16x32_bf16 v[32:35], v[150:153], v[200:203], v[32:35]
	v_mfma_f32_16x16x32_bf16 v[24:27], v[176:179], v[200:203], v[24:27]
	s_setprio 3
	s_barrier
	v_mfma_f32_16x16x32_bf16 v[16:19], v[150:153], v[208:211], v[16:19]
	v_mfma_f32_16x16x32_bf16 v[8:11], v[176:179], v[208:211], v[8:11]
	s_setprio 2
	s_add_u32 s4, s54, 0xc000
	s_addc_u32 s5, s55, 0
	s_add_i32 s54, s72, s28
	s_mov_b32 m0, s54
	s_nop 0
	global_load_lds_dwordx4 v138, s[4:5]
	s_add_i32 m0, s54, 0x2000
	s_nop 0
	global_load_lds_dwordx4 v140, s[4:5]
	s_waitcnt vmcnt(6)
	s_barrier
	s_setprio 0
	v_mfma_f32_16x16x32_bf16 v[60:63], v[212:215], v[180:183], v[60:63]
	v_mfma_f32_16x16x32_bf16 v[52:55], v[220:223], v[180:183], v[52:55]
	v_mfma_f32_16x16x32_bf16 v[44:47], v[212:215], v[188:191], v[44:47]
	v_mfma_f32_16x16x32_bf16 v[36:39], v[220:223], v[188:191], v[36:39]
	v_mfma_f32_16x16x32_bf16 v[28:31], v[212:215], v[196:199], v[28:31]
	v_mfma_f32_16x16x32_bf16 v[20:23], v[220:223], v[196:199], v[20:23]
	v_mfma_f32_16x16x32_bf16 v[12:15], v[212:215], v[204:207], v[12:15]
	v_mfma_f32_16x16x32_bf16 v[4:7], v[220:223], v[204:207], v[4:7]
	v_mfma_f32_16x16x32_bf16 v[60:63], v[216:219], v[184:187], v[60:63]
	v_mfma_f32_16x16x32_bf16 v[52:55], v[224:227], v[184:187], v[52:55]
	v_mfma_f32_16x16x32_bf16 v[44:47], v[216:219], v[192:195], v[44:47]
	v_mfma_f32_16x16x32_bf16 v[36:39], v[224:227], v[192:195], v[36:39]
	v_mfma_f32_16x16x32_bf16 v[28:31], v[216:219], v[200:203], v[28:31]
	v_mfma_f32_16x16x32_bf16 v[20:23], v[224:227], v[200:203], v[20:23]
	v_mfma_f32_16x16x32_bf16 v[12:15], v[216:219], v[208:211], v[12:15]
	v_mfma_f32_16x16x32_bf16 v[4:7], v[224:227], v[208:211], v[4:7]
	s_setprio 2
	s_add_i32 s70, s70, 2
	s_add_u32 s50, s50, 0x10000
	s_addc_u32 s51, s51, 0
	s_add_u32 s45, s45, 0x10000
	s_addc_u32 s47, s47, 0
	s_cmp_gt_u32 s70, 29
	s_barrier
	s_cbranch_scc0 .LBB0_899
	s_setprio 0
	v_mul_f32_e32 v148, 0xbfb8aa3b, v128
	v_mul_f32_e32 v149, 0xbfb8aa3b, v129
	v_exp_f32_e32 v148, v148
	v_exp_f32_e32 v149, v149
	s_lshl_b32 s5, s69, 8
	s_add_i32 s5, s5, s58
	v_add_f32_e32 v148, 1.0, v148
	v_add_f32_e32 v149, 1.0, v149
	v_rcp_f32_e32 v148, v148
	v_rcp_f32_e32 v149, v149
	s_lshl_b32 s4, s68, 7
	s_or_b32 s4, s4, s59
	s_ashr_i32 s45, s5, 8
	v_pk_mul_f32 v[128:129], v[128:129], v[148:149]
	s_ashr_i32 s4, s4, 6
	v_pk_mul_f32 v[124:125], v[128:129], v[124:125]
	s_mulk_i32 s45, 0x58
	v_cvt_pk_bf16_f32 v124, v124, v125
	v_mul_f32_e32 v125, 0xbfb8aa3b, v130
	v_exp_f32_e32 v125, v125
	s_add_i32 s50, s45, s4
	s_ashr_i32 s51, s50, 31
	s_lshl_b64 s[50:51], s[50:51], 15
	v_add_f32_e32 v125, 1.0, v125
	v_rcp_f32_e32 v128, v125
	v_mul_f32_e32 v125, 0xbfb8aa3b, v131
	v_exp_f32_e32 v125, v125
	s_add_u32 s45, s16, s50
	s_addc_u32 s47, s17, s51
	s_lshl_b32 s50, s5, 7
	v_add_f32_e32 v125, 1.0, v125
	v_rcp_f32_e32 v129, v125
	s_and_b32 s50, s50, 0x4000
	s_add_u32 s50, s45, s50
	s_addc_u32 s51, s47, 0
	v_pk_mul_f32 v[128:129], v[130:131], v[128:129]
	s_or_b32 s45, s5, 16
	v_pk_mul_f32 v[126:127], v[128:129], v[126:127]
	s_lshr_b32 s45, s45, 3
	v_cvt_pk_bf16_f32 v125, v126, v127
	v_mul_f32_e32 v126, 0xbfb8aa3b, v120
	v_mul_f32_e32 v127, 0xbfb8aa3b, v121
	v_exp_f32_e32 v126, v126
	v_exp_f32_e32 v127, v127
	v_or_b32_e32 v145, s5, v137
	s_and_b32 s45, s45, 10
	v_add_f32_e32 v126, 1.0, v126
	v_add_f32_e32 v127, 1.0, v127
	v_rcp_f32_e32 v126, v126
	v_rcp_f32_e32 v127, v127
	v_lshlrev_b32_e32 v132, 6, v145
	v_lshlrev_b32_e32 v146, 2, v145
	s_or_b32 s45, s45, s64
	v_pk_mul_f32 v[120:121], v[120:121], v[126:127]
	v_and_or_b32 v132, v132, s15, v142
	v_pk_mul_f32 v[116:117], v[120:121], v[116:117]
	v_and_b32_e32 v146, 32, v146
	v_cvt_pk_bf16_f32 v126, v116, v117
	v_mul_f32_e32 v116, 0xbfb8aa3b, v122
	v_mul_f32_e32 v117, 0xbfb8aa3b, v123
	v_exp_f32_e32 v116, v116
	v_exp_f32_e32 v117, v117
	s_lshl_b32 s45, s45, 10
	v_bitop3_b32 v147, v132, s65, v146 bitop3:0xde
	v_add_f32_e32 v116, 1.0, v116
	v_add_f32_e32 v117, 1.0, v117
	v_rcp_f32_e32 v116, v116
	v_rcp_f32_e32 v117, v117
	s_and_b64 vcc, exec, s[42:43]
	s_mov_b32 s68, s44
	s_mov_b32 s69, s46
	v_pk_mul_f32 v[116:117], v[122:123], v[116:117]
	s_mov_b64 s[54:55], s[40:41]
	v_pk_mul_f32 v[116:117], v[116:117], v[118:119]
	v_bitop3_b32 v118, v132, s45, v146 bitop3:0xde
	v_cvt_pk_bf16_f32 v127, v116, v117
	v_mul_f32_e32 v116, 0xbfb8aa3b, v112
	v_mul_f32_e32 v117, 0xbfb8aa3b, v113
	v_exp_f32_e32 v116, v116
	v_exp_f32_e32 v117, v117
	s_or_b32 s45, s5, 32
	s_or_b32 s5, s5, 48
	v_add_f32_e32 v116, 1.0, v116
	v_add_f32_e32 v117, 1.0, v117
	v_rcp_f32_e32 v116, v116
	v_rcp_f32_e32 v117, v117
	s_lshr_b32 s45, s45, 3
	s_lshr_b32 s5, s5, 3
	s_and_b32 s45, s45, 12
	v_pk_mul_f32 v[112:113], v[112:113], v[116:117]
	s_and_b32 s5, s5, 14
	v_pk_mul_f32 v[108:109], v[112:113], v[108:109]
	s_or_b32 s45, s45, s64
	v_cvt_pk_bf16_f32 v108, v108, v109
; __device__ __forceinline__ unsigned cvt_pk_bf16(float lo, float hi) { f32x2 v = {lo, hi}; bf16x2v b = __builtin_convertvector(v, bf16x2v); return __builtin_bit_cast(unsigned, b); }
; __device__ __forceinline__ float silu_f(float x) { return x * __builtin_amdgcn_rcpf(1.f + __expf(-x)); }
;     __device__ __forceinline__ void operator()(const f32x4 (&acc)[2][2][4][2], const Unit& u, int wr, int wc, int fr, int fq) const {
;     ...
;                 bf16_t* rowp = O + img_off(row0 + ai * HALF + m * 16, col0, D_FF / 64);
;                 const f32x4 g0 = acc[ai][0][m][0], g1 = acc[ai][0][m][1], u0 = acc[ai][1][m][0], u1 = acc[ai][1][m][1];
;                 u32x4 w;
;                 w.x = cvt_pk_bf16(silu_f(g0[0]) * u0[0], silu_f(g0[1]) * u0[1]); w.y = cvt_pk_bf16(silu_f(g0[2]) * u0[2], silu_f(g0[3]) * u0[3]);
;                 w.z = cvt_pk_bf16(silu_f(g1[0]) * u1[0], silu_f(g1[1]) * u1[1]); w.w = cvt_pk_bf16(silu_f(g1[2]) * u1[2], silu_f(g1[3]) * u1[3]);
;                 *(u32x4*)rowp = w;
	v_mul_f32_e32 v109, 0xbfb8aa3b, v114
	v_exp_f32_e32 v109, v109
	s_or_b32 s5, s5, s64
	s_lshl_b32 s45, s45, 10
	s_lshl_b32 s5, s5, 10
	v_add_f32_e32 v109, 1.0, v109
	v_rcp_f32_e32 v112, v109
	v_mul_f32_e32 v109, 0xbfb8aa3b, v115
	v_exp_f32_e32 v109, v109
	global_store_dwordx4 v147, v[124:127], s[50:51]
	v_add_f32_e32 v109, 1.0, v109
	v_rcp_f32_e32 v113, v109
	s_nop 0
	v_pk_mul_f32 v[112:113], v[114:115], v[112:113]
	s_nop 0
	v_pk_mul_f32 v[110:111], v[112:113], v[110:111]
	s_nop 0
	v_cvt_pk_bf16_f32 v109, v110, v111
	v_mul_f32_e32 v110, 0xbfb8aa3b, v104
	v_mul_f32_e32 v111, 0xbfb8aa3b, v105
	v_exp_f32_e32 v110, v110
	v_exp_f32_e32 v111, v111
	v_add_f32_e32 v110, 1.0, v110
	v_add_f32_e32 v111, 1.0, v111
	v_rcp_f32_e32 v110, v110
	v_rcp_f32_e32 v111, v111
	s_nop 0
	v_pk_mul_f32 v[104:105], v[104:105], v[110:111]
	s_nop 0
	v_pk_mul_f32 v[100:101], v[104:105], v[100:101]
	s_nop 0
	v_cvt_pk_bf16_f32 v110, v100, v101
	v_mul_f32_e32 v100, 0xbfb8aa3b, v106
	v_mul_f32_e32 v101, 0xbfb8aa3b, v107
	v_exp_f32_e32 v100, v100
	v_exp_f32_e32 v101, v101
	v_add_f32_e32 v100, 1.0, v100
	v_add_f32_e32 v101, 1.0, v101
	v_rcp_f32_e32 v100, v100
	v_rcp_f32_e32 v101, v101
	s_nop 0
	v_pk_mul_f32 v[100:101], v[106:107], v[100:101]
	s_nop 0
	v_pk_mul_f32 v[100:101], v[100:101], v[102:103]
	v_bitop3_b32 v102, v132, s45, v146 bitop3:0xde
	v_cvt_pk_bf16_f32 v111, v100, v101
	v_mul_f32_e32 v100, 0xbfb8aa3b, v96
	v_mul_f32_e32 v101, 0xbfb8aa3b, v97
	v_exp_f32_e32 v100, v100
	v_exp_f32_e32 v101, v101
	global_store_dwordx4 v118, v[108:111], s[50:51]
	v_add_f32_e32 v100, 1.0, v100
	v_add_f32_e32 v101, 1.0, v101
	v_rcp_f32_e32 v100, v100
	v_rcp_f32_e32 v101, v101
	s_nop 0
	v_pk_mul_f32 v[96:97], v[96:97], v[100:101]
	s_nop 0
	v_pk_mul_f32 v[92:93], v[96:97], v[92:93]
	s_nop 0
	v_cvt_pk_bf16_f32 v92, v92, v93
	v_mul_f32_e32 v93, 0xbfb8aa3b, v98
	v_exp_f32_e32 v93, v93
	s_nop 0
	v_add_f32_e32 v93, 1.0, v93
	v_rcp_f32_e32 v96, v93
	v_mul_f32_e32 v93, 0xbfb8aa3b, v99
	v_exp_f32_e32 v93, v93
	s_nop 0
	v_add_f32_e32 v93, 1.0, v93
	v_rcp_f32_e32 v97, v93
	s_nop 0
	v_pk_mul_f32 v[96:97], v[98:99], v[96:97]
	s_nop 0
	v_pk_mul_f32 v[94:95], v[96:97], v[94:95]
	s_nop 0
	v_cvt_pk_bf16_f32 v93, v94, v95
	v_mul_f32_e32 v94, 0xbfb8aa3b, v88
	v_mul_f32_e32 v95, 0xbfb8aa3b, v89
	v_exp_f32_e32 v94, v94
	v_exp_f32_e32 v95, v95
	v_add_f32_e32 v94, 1.0, v94
	v_add_f32_e32 v95, 1.0, v95
	v_rcp_f32_e32 v94, v94
	v_rcp_f32_e32 v95, v95
	s_nop 0
	v_pk_mul_f32 v[88:89], v[88:89], v[94:95]
	s_nop 0
	v_pk_mul_f32 v[84:85], v[88:89], v[84:85]
	s_nop 0
	v_cvt_pk_bf16_f32 v94, v84, v85
	v_mul_f32_e32 v84, 0xbfb8aa3b, v90
	v_mul_f32_e32 v85, 0xbfb8aa3b, v91
	v_exp_f32_e32 v84, v84
	v_exp_f32_e32 v85, v85
	v_add_f32_e32 v84, 1.0, v84
	v_add_f32_e32 v85, 1.0, v85
	v_rcp_f32_e32 v84, v84
	v_rcp_f32_e32 v85, v85
	s_nop 0
	v_pk_mul_f32 v[84:85], v[90:91], v[84:85]
	s_nop 0
	v_pk_mul_f32 v[84:85], v[84:85], v[86:87]
	v_bitop3_b32 v86, v132, s5, v146 bitop3:0xde
	v_cvt_pk_bf16_f32 v95, v84, v85
	v_mul_f32_e32 v84, 0xbfb8aa3b, v80
	v_mul_f32_e32 v85, 0xbfb8aa3b, v81
	v_exp_f32_e32 v84, v84
	v_exp_f32_e32 v85, v85
	global_store_dwordx4 v102, v[92:95], s[50:51]
	v_add_f32_e32 v84, 1.0, v84
	v_add_f32_e32 v85, 1.0, v85
	v_rcp_f32_e32 v84, v84
	v_rcp_f32_e32 v85, v85
	s_nop 0
	v_pk_mul_f32 v[80:81], v[80:81], v[84:85]
	s_nop 0
	v_pk_mul_f32 v[76:77], v[80:81], v[76:77]
	s_nop 0
	v_cvt_pk_bf16_f32 v76, v76, v77
	v_mul_f32_e32 v77, 0xbfb8aa3b, v82
	v_exp_f32_e32 v77, v77
	s_nop 0
	v_add_f32_e32 v77, 1.0, v77
	v_rcp_f32_e32 v80, v77
	v_mul_f32_e32 v77, 0xbfb8aa3b, v83
	v_exp_f32_e32 v77, v77
	s_nop 0
	v_add_f32_e32 v77, 1.0, v77
	v_rcp_f32_e32 v81, v77
	s_nop 0
	v_pk_mul_f32 v[80:81], v[82:83], v[80:81]
	s_nop 0
	v_pk_mul_f32 v[78:79], v[80:81], v[78:79]
	s_nop 0
	v_cvt_pk_bf16_f32 v77, v78, v79
	v_mul_f32_e32 v78, 0xbfb8aa3b, v72
	v_mul_f32_e32 v79, 0xbfb8aa3b, v73
	v_exp_f32_e32 v78, v78
	v_exp_f32_e32 v79, v79
	v_add_f32_e32 v78, 1.0, v78
	v_add_f32_e32 v79, 1.0, v79
	v_rcp_f32_e32 v78, v78
	v_rcp_f32_e32 v79, v79
	s_nop 0
	v_pk_mul_f32 v[72:73], v[72:73], v[78:79]
	s_nop 0
	v_pk_mul_f32 v[68:69], v[72:73], v[68:69]
	v_mul_f32_e32 v73, 0xbfb8aa3b, v65
	v_cvt_pk_bf16_f32 v78, v68, v69
	v_mul_f32_e32 v68, 0xbfb8aa3b, v74
	v_mul_f32_e32 v69, 0xbfb8aa3b, v75
	v_exp_f32_e32 v68, v68
	v_exp_f32_e32 v69, v69
	v_exp_f32_e32 v73, v73
	v_add_f32_e32 v68, 1.0, v68
	v_add_f32_e32 v69, 1.0, v69
	v_rcp_f32_e32 v68, v68
	v_rcp_f32_e32 v69, v69
	v_add_f32_e32 v73, 1.0, v73
	v_rcp_f32_e32 v73, v73
	v_pk_mul_f32 v[68:69], v[74:75], v[68:69]
	s_nop 0
	v_pk_mul_f32 v[68:69], v[68:69], v[70:71]
	v_add_u32_e32 v70, 0x80, v145
	v_lshlrev_b32_e32 v71, 6, v70
	v_lshlrev_b32_e32 v72, 2, v70
	v_and_or_b32 v71, v71, s15, v142
	v_and_b32_e32 v72, 32, v72
	v_bitop3_b32 v132, v71, s65, v72 bitop3:0xde
	v_mul_f32_e32 v72, 0xbfb8aa3b, v64
	v_exp_f32_e32 v72, v72
	v_cvt_pk_bf16_f32 v79, v68, v69
	v_lshrrev_b32_e32 v68, 8, v70
	v_mov_b32_e32 v69, s4
	v_add_f32_e32 v72, 1.0, v72
	v_rcp_f32_e32 v72, v72
	s_movk_i32 s4, 0x58
	v_mad_i32_i24 v68, v68, s4, v69
	v_ashrrev_i32_e32 v69, 31, v68
	v_pk_mul_f32 v[64:65], v[64:65], v[72:73]
	v_lshlrev_b64 v[68:69], 15, v[68:69]
	v_pk_mul_f32 v[60:61], v[64:65], v[60:61]
	v_lshlrev_b32_e32 v70, 7, v70
	v_cvt_pk_bf16_f32 v60, v60, v61
	v_mul_f32_e32 v61, 0xbfb8aa3b, v66
	v_exp_f32_e32 v61, v61
	v_lshl_add_u64 v[68:69], s[16:17], 0, v[68:69]
	v_and_b32_e32 v70, 0x4000, v70
	v_mov_b32_e32 v71, v133
	v_add_f32_e32 v61, 1.0, v61
	v_rcp_f32_e32 v64, v61
	v_mul_f32_e32 v61, 0xbfb8aa3b, v67
	v_exp_f32_e32 v61, v61
	v_lshl_add_u64 v[70:71], v[68:69], 0, v[70:71]
	v_lshl_add_u64 v[70:71], v[70:71], 0, v[132:133]
; __device__ __forceinline__ unsigned cvt_pk_bf16(float lo, float hi) { f32x2 v = {lo, hi}; bf16x2v b = __builtin_convertvector(v, bf16x2v); return __builtin_bit_cast(unsigned, b); }
; __device__ __forceinline__ float silu_f(float x) { return x * __builtin_amdgcn_rcpf(1.f + __expf(-x)); }
;     __device__ __forceinline__ void operator()(const f32x4 (&acc)[2][2][4][2], const Unit& u, int wr, int wc, int fr, int fq) const {
;     ...
;                 bf16_t* rowp = O + img_off(row0 + ai * HALF + m * 16, col0, D_FF / 64);
;                 const f32x4 g0 = acc[ai][0][m][0], g1 = acc[ai][0][m][1], u0 = acc[ai][1][m][0], u1 = acc[ai][1][m][1];
;                 u32x4 w;
;                 w.x = cvt_pk_bf16(silu_f(g0[0]) * u0[0], silu_f(g0[1]) * u0[1]); w.y = cvt_pk_bf16(silu_f(g0[2]) * u0[2], silu_f(g0[3]) * u0[3]);
;                 w.z = cvt_pk_bf16(silu_f(g1[0]) * u1[0], silu_f(g1[1]) * u1[1]); w.w = cvt_pk_bf16(silu_f(g1[2]) * u1[2], silu_f(g1[3]) * u1[3]);
;                 *(u32x4*)rowp = w;
	s_mov_b64 s[4:5], s[48:49]
	v_add_f32_e32 v61, 1.0, v61
	v_rcp_f32_e32 v65, v61
	global_store_dwordx4 v86, v[76:79], s[50:51]
	v_pk_mul_f32 v[64:65], v[66:67], v[64:65]
	s_nop 0
	v_pk_mul_f32 v[62:63], v[64:65], v[62:63]
	s_nop 0
	v_cvt_pk_bf16_f32 v61, v62, v63
	v_mul_f32_e32 v62, 0xbfb8aa3b, v56
	v_mul_f32_e32 v63, 0xbfb8aa3b, v57
	v_exp_f32_e32 v62, v62
	v_exp_f32_e32 v63, v63
	v_add_f32_e32 v62, 1.0, v62
	v_add_f32_e32 v63, 1.0, v63
	v_rcp_f32_e32 v62, v62
	v_rcp_f32_e32 v63, v63
	s_nop 0
	v_pk_mul_f32 v[56:57], v[56:57], v[62:63]
	s_nop 0
	v_pk_mul_f32 v[52:53], v[56:57], v[52:53]
	s_nop 0
	v_cvt_pk_bf16_f32 v62, v52, v53
	v_mul_f32_e32 v52, 0xbfb8aa3b, v58
	v_mul_f32_e32 v53, 0xbfb8aa3b, v59
	v_exp_f32_e32 v52, v52
	v_exp_f32_e32 v53, v53
	v_add_f32_e32 v52, 1.0, v52
	v_add_f32_e32 v53, 1.0, v53
	v_rcp_f32_e32 v52, v52
	v_rcp_f32_e32 v53, v53
	s_nop 0
	v_pk_mul_f32 v[52:53], v[58:59], v[52:53]
	s_nop 0
	v_pk_mul_f32 v[52:53], v[52:53], v[54:55]
	s_nop 0
	v_cvt_pk_bf16_f32 v63, v52, v53
	v_add_u32_e32 v52, 0x90, v145
	v_lshrrev_b32_e32 v54, 3, v52
	v_lshlrev_b32_e32 v53, 6, v52
	v_and_or_b32 v54, v54, 10, s64
	v_lshlrev_b32_e32 v55, 2, v52
	v_and_or_b32 v53, v53, s15, v142
	v_lshlrev_b32_e32 v54, 10, v54
	v_and_b32_e32 v55, 32, v55
	v_bitop3_b32 v132, v53, v54, v55 bitop3:0xde
	v_mul_f32_e32 v54, 0xbfb8aa3b, v48
	v_mul_f32_e32 v55, 0xbfb8aa3b, v49
	v_exp_f32_e32 v54, v54
	v_exp_f32_e32 v55, v55
	v_lshlrev_b32_e32 v52, 7, v52
	v_and_b32_e32 v52, 0x4000, v52
	v_add_f32_e32 v54, 1.0, v54
	v_add_f32_e32 v55, 1.0, v55
	v_rcp_f32_e32 v54, v54
	v_rcp_f32_e32 v55, v55
	v_mov_b32_e32 v53, v133
	v_lshl_add_u64 v[52:53], v[68:69], 0, v[52:53]
	v_lshl_add_u64 v[52:53], v[52:53], 0, v[132:133]
	v_pk_mul_f32 v[48:49], v[48:49], v[54:55]
	global_store_dwordx4 v[70:71], v[60:63], off
	v_pk_mul_f32 v[44:45], v[48:49], v[44:45]
	s_nop 0
	v_cvt_pk_bf16_f32 v44, v44, v45
	v_mul_f32_e32 v45, 0xbfb8aa3b, v50
	v_exp_f32_e32 v45, v45
	s_nop 0
	v_add_f32_e32 v45, 1.0, v45
	v_rcp_f32_e32 v48, v45
	v_mul_f32_e32 v45, 0xbfb8aa3b, v51
	v_exp_f32_e32 v45, v45
	s_nop 0
	v_add_f32_e32 v45, 1.0, v45
	v_rcp_f32_e32 v49, v45
	s_nop 0
	v_pk_mul_f32 v[48:49], v[50:51], v[48:49]
	s_nop 0
	v_pk_mul_f32 v[46:47], v[48:49], v[46:47]
	s_nop 0
	v_cvt_pk_bf16_f32 v45, v46, v47
	v_mul_f32_e32 v46, 0xbfb8aa3b, v40
	v_mul_f32_e32 v47, 0xbfb8aa3b, v41
	v_exp_f32_e32 v46, v46
	v_exp_f32_e32 v47, v47
	v_add_f32_e32 v46, 1.0, v46
	v_add_f32_e32 v47, 1.0, v47
	v_rcp_f32_e32 v46, v46
	v_rcp_f32_e32 v47, v47
	s_nop 0
	v_pk_mul_f32 v[40:41], v[40:41], v[46:47]
	s_nop 0
	v_pk_mul_f32 v[36:37], v[40:41], v[36:37]
	s_nop 0
	v_cvt_pk_bf16_f32 v46, v36, v37
	v_mul_f32_e32 v36, 0xbfb8aa3b, v42
	v_mul_f32_e32 v37, 0xbfb8aa3b, v43
	v_exp_f32_e32 v36, v36
	v_exp_f32_e32 v37, v37
	v_add_f32_e32 v36, 1.0, v36
	v_add_f32_e32 v37, 1.0, v37
	v_rcp_f32_e32 v36, v36
	v_rcp_f32_e32 v37, v37
	s_nop 0
	v_pk_mul_f32 v[36:37], v[42:43], v[36:37]
	s_nop 0
	v_pk_mul_f32 v[36:37], v[36:37], v[38:39]
	s_nop 0
	v_cvt_pk_bf16_f32 v47, v36, v37
	v_add_u32_e32 v36, 0xa0, v145
	v_lshrrev_b32_e32 v38, 3, v36
	v_lshlrev_b32_e32 v37, 6, v36
	v_and_or_b32 v38, v38, 12, s64
	v_lshlrev_b32_e32 v39, 2, v36
	v_and_or_b32 v37, v37, s15, v142
	v_lshlrev_b32_e32 v38, 10, v38
	v_and_b32_e32 v39, 32, v39
	v_bitop3_b32 v132, v37, v38, v39 bitop3:0xde
	v_mul_f32_e32 v38, 0xbfb8aa3b, v32
	v_mul_f32_e32 v39, 0xbfb8aa3b, v33
	v_exp_f32_e32 v38, v38
	v_exp_f32_e32 v39, v39
	v_lshlrev_b32_e32 v36, 7, v36
	v_and_b32_e32 v36, 0x4000, v36
	v_add_f32_e32 v38, 1.0, v38
	v_add_f32_e32 v39, 1.0, v39
	v_rcp_f32_e32 v38, v38
; __device__ __forceinline__ unsigned cvt_pk_bf16(float lo, float hi) { f32x2 v = {lo, hi}; bf16x2v b = __builtin_convertvector(v, bf16x2v); return __builtin_bit_cast(unsigned, b); }
; __device__ __forceinline__ float silu_f(float x) { return x * __builtin_amdgcn_rcpf(1.f + __expf(-x)); }
; #define PG8_WAIT_V(n) asm volatile("s_waitcnt vmcnt(" #n ")" ::: "memory")
; #define PG8_BAR __builtin_amdgcn_s_barrier()
;     __device__ __forceinline__ void operator()(const f32x4 (&acc)[2][2][4][2], const Unit& u, int wr, int wc, int fr, int fq) const {
;     ...
;                 bf16_t* rowp = O + img_off(row0 + ai * HALF + m * 16, col0, D_FF / 64);
;                 const f32x4 g0 = acc[ai][0][m][0], g1 = acc[ai][0][m][1], u0 = acc[ai][1][m][0], u1 = acc[ai][1][m][1];
;                 u32x4 w;
;                 w.x = cvt_pk_bf16(silu_f(g0[0]) * u0[0], silu_f(g0[1]) * u0[1]); w.y = cvt_pk_bf16(silu_f(g0[2]) * u0[2], silu_f(g0[3]) * u0[3]);
;                 w.z = cvt_pk_bf16(silu_f(g1[0]) * u1[0], silu_f(g1[1]) * u1[1]); w.w = cvt_pk_bf16(silu_f(g1[2]) * u1[2], silu_f(g1[3]) * u1[3]);
;                 *(u32x4*)rowp = w;
; template <class Epi, class Sched, int LD>
; __device__ __forceinline__ void gemm_phase(LAS unsigned char* lds, const Gemm g, const Sched& S, const Epi& E) {
;     ...
;         if (!has_next) break;
; #pragma unroll
;         for (int a = 0; a < 2; ++a)
; #pragma unroll
;             for (int b = 0; b < 2; ++b)
; #pragma unroll
;                 for (int m = 0; m < 4; ++m)
; #pragma unroll
;                     for (int n = 0; n < 2; ++n) acc[a][b][m][n] = (f32x4){0.f, 0.f, 0.f, 0.f};
;         cur = nxt; cA = nA; cB = nB; ++ui;
;     }
;     PG8_WAIT_V(0);
;     if (wr == 0) PG8_BAR;
;     PG8_BAR;
	v_rcp_f32_e32 v39, v39
	v_mov_b32_e32 v37, v133
	v_lshl_add_u64 v[36:37], v[68:69], 0, v[36:37]
	v_lshl_add_u64 v[36:37], v[36:37], 0, v[132:133]
	v_pk_mul_f32 v[32:33], v[32:33], v[38:39]
	global_store_dwordx4 v[52:53], v[44:47], off
	v_pk_mul_f32 v[28:29], v[32:33], v[28:29]
	s_nop 0
	v_cvt_pk_bf16_f32 v28, v28, v29
	v_mul_f32_e32 v29, 0xbfb8aa3b, v34
	v_exp_f32_e32 v29, v29
	s_nop 0
	v_add_f32_e32 v29, 1.0, v29
	v_rcp_f32_e32 v32, v29
	v_mul_f32_e32 v29, 0xbfb8aa3b, v35
	v_exp_f32_e32 v29, v29
	s_nop 0
	v_add_f32_e32 v29, 1.0, v29
	v_rcp_f32_e32 v33, v29
	s_nop 0
	v_pk_mul_f32 v[32:33], v[34:35], v[32:33]
	s_nop 0
	v_pk_mul_f32 v[30:31], v[32:33], v[30:31]
	s_nop 0
	v_cvt_pk_bf16_f32 v29, v30, v31
	v_mul_f32_e32 v30, 0xbfb8aa3b, v24
	v_mul_f32_e32 v31, 0xbfb8aa3b, v25
	v_exp_f32_e32 v30, v30
	v_exp_f32_e32 v31, v31
	v_add_f32_e32 v30, 1.0, v30
	v_add_f32_e32 v31, 1.0, v31
	v_rcp_f32_e32 v30, v30
	v_rcp_f32_e32 v31, v31
	s_nop 0
	v_pk_mul_f32 v[24:25], v[24:25], v[30:31]
	s_nop 0
	v_pk_mul_f32 v[20:21], v[24:25], v[20:21]
	s_nop 0
	v_cvt_pk_bf16_f32 v30, v20, v21
	v_mul_f32_e32 v20, 0xbfb8aa3b, v26
	v_mul_f32_e32 v21, 0xbfb8aa3b, v27
	v_exp_f32_e32 v20, v20
	v_exp_f32_e32 v21, v21
	v_add_f32_e32 v20, 1.0, v20
	v_add_f32_e32 v21, 1.0, v21
	v_rcp_f32_e32 v20, v20
	v_rcp_f32_e32 v21, v21
	s_nop 0
	v_pk_mul_f32 v[20:21], v[26:27], v[20:21]
	s_nop 0
	v_pk_mul_f32 v[20:21], v[20:21], v[22:23]
	s_nop 0
	v_cvt_pk_bf16_f32 v31, v20, v21
	v_add_u32_e32 v20, 0xb0, v145
	v_lshrrev_b32_e32 v22, 3, v20
	v_lshlrev_b32_e32 v21, 6, v20
	v_and_or_b32 v22, v22, 14, s64
	v_lshlrev_b32_e32 v23, 2, v20
	v_and_or_b32 v21, v21, s15, v142
	v_lshlrev_b32_e32 v22, 10, v22
	v_and_b32_e32 v23, 32, v23
	v_bitop3_b32 v132, v21, v22, v23 bitop3:0xde
	v_mul_f32_e32 v22, 0xbfb8aa3b, v16
	v_mul_f32_e32 v23, 0xbfb8aa3b, v17
	v_exp_f32_e32 v22, v22
	v_exp_f32_e32 v23, v23
	v_lshlrev_b32_e32 v20, 7, v20
	v_and_b32_e32 v20, 0x4000, v20
	v_add_f32_e32 v22, 1.0, v22
	v_add_f32_e32 v23, 1.0, v23
	v_rcp_f32_e32 v22, v22
	v_rcp_f32_e32 v23, v23
	v_mov_b32_e32 v21, v133
	v_lshl_add_u64 v[20:21], v[68:69], 0, v[20:21]
	v_lshl_add_u64 v[20:21], v[20:21], 0, v[132:133]
	v_pk_mul_f32 v[16:17], v[16:17], v[22:23]
	global_store_dwordx4 v[36:37], v[28:31], off
	v_pk_mul_f32 v[12:13], v[16:17], v[12:13]
	s_nop 0
	v_cvt_pk_bf16_f32 v12, v12, v13
	v_mul_f32_e32 v13, 0xbfb8aa3b, v18
	v_exp_f32_e32 v13, v13
	s_nop 0
	v_add_f32_e32 v13, 1.0, v13
	v_rcp_f32_e32 v16, v13
	v_mul_f32_e32 v13, 0xbfb8aa3b, v19
	v_exp_f32_e32 v13, v13
	s_nop 0
	v_add_f32_e32 v13, 1.0, v13
	v_rcp_f32_e32 v17, v13
	s_nop 0
	v_pk_mul_f32 v[16:17], v[18:19], v[16:17]
	s_nop 0
	v_pk_mul_f32 v[14:15], v[16:17], v[14:15]
	s_nop 0
	v_cvt_pk_bf16_f32 v13, v14, v15
	v_mul_f32_e32 v14, 0xbfb8aa3b, v8
	v_mul_f32_e32 v15, 0xbfb8aa3b, v9
	v_exp_f32_e32 v14, v14
	v_exp_f32_e32 v15, v15
	v_add_f32_e32 v14, 1.0, v14
	v_add_f32_e32 v15, 1.0, v15
	v_rcp_f32_e32 v14, v14
	v_rcp_f32_e32 v15, v15
	s_nop 0
	v_pk_mul_f32 v[8:9], v[8:9], v[14:15]
	s_nop 0
	v_pk_mul_f32 v[4:5], v[8:9], v[4:5]
	s_nop 0
	v_cvt_pk_bf16_f32 v14, v4, v5
	v_mul_f32_e32 v4, 0xbfb8aa3b, v10
	v_mul_f32_e32 v5, 0xbfb8aa3b, v11
	v_exp_f32_e32 v4, v4
	v_exp_f32_e32 v5, v5
	v_add_f32_e32 v4, 1.0, v4
	v_add_f32_e32 v5, 1.0, v5
	v_rcp_f32_e32 v4, v4
	v_rcp_f32_e32 v5, v5
	s_nop 0
	v_pk_mul_f32 v[4:5], v[10:11], v[4:5]
	s_nop 0
	v_pk_mul_f32 v[4:5], v[4:5], v[6:7]
	s_nop 0
	v_cvt_pk_bf16_f32 v15, v4, v5
	global_store_dwordx4 v[20:21], v[12:15], off
	s_cbranch_vccz .LBB0_892
	s_waitcnt vmcnt(0)
	s_cmpk_gt_u32 s2, 0xff
	s_cbranch_scc1 .LBB0_903
	s_barrier
